# adaLN norm phases rewritten: all 8 rows per wave loaded up front, scale/shift staged in LDS once per workgroup, DPP+readlane row sums
# speedup vs baseline: 1.0136x; 1.0136x over previous
.LBB0_104:
	v_readlane_b32 s22, v253, 33
	v_readlane_b32 s16, v254, 22
	v_readlane_b32 s17, v254, 23
	v_lshlrev_b32_e32 v182, 4, v192
	v_lshlrev_b32_e32 v183, 3, v192
	s_and_b32 s23, s22, 3
	s_lshl_b32 s23, s23, 10
	s_bitcmp1_b32 s22, 2
	s_mov_b32 s18, 0x1000
	s_cselect_b32 s18, 0x0, s18
	s_add_u32 s23, s23, s18
	s_add_u32 s16, s16, s23
	s_addc_u32 s17, s17, 0
	s_and_b32 s18, s22, 7
	s_lshl_b32 s18, s18, 10
	v_add_u32_e32 v185, s18, v182
	v_add_u32_e32 v185, 0x4000, v185
	v_add_u32_e32 v184, 0x4000, v182
	v_readfirstlane_b32 s12, v76
	v_readfirstlane_b32 s13, v77
	s_lshl_b32 s23, s22, 12
	s_add_u32 s12, s12, s23
	s_addc_u32 s13, s13, 0
	s_lshl_b32 s23, s22, 11
	s_add_u32 s14, s0, s23
	s_addc_u32 s15, s1, 0
	s_add_u32 s14, s14, 0x3200000
	s_addc_u32 s15, s15, 0
	global_load_dwordx4 v[144:147], v182, s[16:17]
	s_add_u32 s16, s16, 0x6000
	s_addc_u32 s17, s17, 0
	global_load_dwordx4 v[148:151], v182, s[16:17]
	s_add_u32 s16, s16, 0x6000
	s_addc_u32 s17, s17, 0
	global_load_dwordx4 v[152:155], v182, s[16:17]
	s_add_u32 s16, s16, 0x6000
	s_addc_u32 s17, s17, 0
	global_load_dwordx4 v[156:159], v182, s[16:17]
	s_add_u32 s16, s16, 0x6000
	s_addc_u32 s17, s17, 0
	global_load_dwordx4 v[160:163], v182, s[16:17]
	s_add_u32 s16, s16, 0x6000
	s_addc_u32 s17, s17, 0
	global_load_dwordx4 v[164:167], v182, s[16:17]
	s_add_u32 s16, s16, 0x6000
	s_addc_u32 s17, s17, 0
	global_load_dwordx4 v[168:171], v182, s[16:17]
	s_add_u32 s16, s16, 0x6000
	s_addc_u32 s17, s17, 0
	global_load_dwordx4 v[172:175], v182, s[16:17]
	global_load_dwordx4 v[16:19], v182, s[12:13] offset:0
	global_load_dwordx4 v[20:23], v182, s[12:13] offset:1024
	global_load_dwordx4 v[24:27], v182, s[12:13] offset:2048
	global_load_dwordx4 v[28:31], v182, s[12:13] offset:3072
	s_add_u32 s12, s12, 0x800000
	s_addc_u32 s13, s13, 0
	global_load_dwordx4 v[32:35], v182, s[12:13] offset:0
	global_load_dwordx4 v[36:39], v182, s[12:13] offset:1024
	global_load_dwordx4 v[40:43], v182, s[12:13] offset:2048
	global_load_dwordx4 v[44:47], v182, s[12:13] offset:3072
	s_add_u32 s12, s12, 0x800000
	s_addc_u32 s13, s13, 0
	global_load_dwordx4 v[48:51], v182, s[12:13] offset:0
	global_load_dwordx4 v[52:55], v182, s[12:13] offset:1024
	global_load_dwordx4 v[56:59], v182, s[12:13] offset:2048
	global_load_dwordx4 v[60:63], v182, s[12:13] offset:3072
	s_add_u32 s12, s12, 0x800000
	s_addc_u32 s13, s13, 0
	global_load_dwordx4 v[64:67], v182, s[12:13] offset:0
	global_load_dwordx4 v[68:71], v182, s[12:13] offset:1024
	global_load_dwordx4 v[72:75], v182, s[12:13] offset:2048
	global_load_dwordx4 v[76:79], v182, s[12:13] offset:3072
	s_add_u32 s12, s12, 0x800000
	s_addc_u32 s13, s13, 0
	global_load_dwordx4 v[80:83], v182, s[12:13] offset:0
	global_load_dwordx4 v[84:87], v182, s[12:13] offset:1024
	global_load_dwordx4 v[88:91], v182, s[12:13] offset:2048
	global_load_dwordx4 v[92:95], v182, s[12:13] offset:3072
	s_add_u32 s12, s12, 0x800000
	s_addc_u32 s13, s13, 0
	global_load_dwordx4 v[96:99], v182, s[12:13] offset:0
	global_load_dwordx4 v[100:103], v182, s[12:13] offset:1024
	global_load_dwordx4 v[104:107], v182, s[12:13] offset:2048
	global_load_dwordx4 v[108:111], v182, s[12:13] offset:3072
	s_add_u32 s12, s12, 0x800000
	s_addc_u32 s13, s13, 0
	global_load_dwordx4 v[112:115], v182, s[12:13] offset:0
	global_load_dwordx4 v[116:119], v182, s[12:13] offset:1024
	global_load_dwordx4 v[120:123], v182, s[12:13] offset:2048
	global_load_dwordx4 v[124:127], v182, s[12:13] offset:3072
	s_add_u32 s12, s12, 0x800000
	s_addc_u32 s13, s13, 0
	global_load_dwordx4 v[128:131], v182, s[12:13] offset:0
	global_load_dwordx4 v[132:135], v182, s[12:13] offset:1024
	global_load_dwordx4 v[136:139], v182, s[12:13] offset:2048
	global_load_dwordx4 v[140:143], v182, s[12:13] offset:3072
	s_barrier
	s_waitcnt vmcnt(32)
	ds_write_b128 v185, v[144:147] offset:0
	ds_write_b128 v185, v[148:151] offset:8192
	ds_write_b128 v185, v[152:155] offset:16384
	ds_write_b128 v185, v[156:159] offset:24576
	ds_write_b128 v185, v[160:163] offset:32768
	ds_write_b128 v185, v[164:167] offset:40960
	ds_write_b128 v185, v[168:171] offset:49152
	ds_write_b128 v185, v[172:175] offset:57344
	s_waitcnt lgkmcnt(0)
	s_barrier
	s_waitcnt vmcnt(28)
	ds_read_b128 v[144:147], v184 offset:0
	ds_read_b128 v[148:151], v184 offset:1024
	ds_read_b128 v[152:155], v184 offset:2048
	ds_read_b128 v[156:159], v184 offset:3072
	ds_read_b128 v[160:163], v184 offset:4096
	ds_read_b128 v[164:167], v184 offset:5120
	ds_read_b128 v[168:171], v184 offset:6144
	ds_read_b128 v[172:175], v184 offset:7168
	v_mul_f32_e32 v176, v17, v17
	v_mul_f32_e32 v177, v21, v21
	v_mul_f32_e32 v178, v25, v25
	v_mul_f32_e32 v179, v29, v29
	v_fmac_f32_e32 v176, v16, v16
	v_fmac_f32_e32 v177, v20, v20
	v_fmac_f32_e32 v178, v24, v24
	v_fmac_f32_e32 v179, v28, v28
	v_fmac_f32_e32 v176, v18, v18
	v_fmac_f32_e32 v177, v22, v22
	v_fmac_f32_e32 v178, v26, v26
	v_fmac_f32_e32 v179, v30, v30
	v_fmac_f32_e32 v176, v19, v19
	v_fmac_f32_e32 v177, v23, v23
	v_fmac_f32_e32 v178, v27, v27
	v_fmac_f32_e32 v179, v31, v31
	v_add_f32_e32 v176, v177, v176
	v_add_f32_e32 v176, v178, v176
	v_add_f32_e32 v176, v179, v176
	s_nop 1
	v_add_f32_dpp v176, v176, v176 quad_perm:[1,0,3,2] row_mask:0xf bank_mask:0xf
	s_nop 1
	v_add_f32_dpp v176, v176, v176 quad_perm:[2,3,0,1] row_mask:0xf bank_mask:0xf
	s_nop 1
	v_add_f32_dpp v176, v176, v176 row_half_mirror row_mask:0xf bank_mask:0xf
	s_nop 1
	v_add_f32_dpp v176, v176, v176 row_mirror row_mask:0xf bank_mask:0xf
	s_nop 1
	v_readlane_b32 s18, v176, 0
	v_readlane_b32 s19, v176, 16
	v_readlane_b32 s20, v176, 32
	v_readlane_b32 s21, v176, 48
	s_nop 1
	v_mov_b32_e32 v177, s19
	v_mov_b32_e32 v178, s21
	v_add_f32_e32 v177, s18, v177
	v_add_f32_e32 v178, s20, v178
	v_add_f32_e32 v176, v177, v178
	v_fmamk_f32 v176, v176, 0x3a800000, v210
	v_rsq_f32_e32 v180, v176
	s_nop 0
	v_pk_mul_f32 v[16:17], v[16:17], v[180:181] op_sel_hi:[1,0]
	v_pk_mul_f32 v[18:19], v[18:19], v[180:181] op_sel_hi:[1,0]
	v_pk_mul_f32 v[20:21], v[20:21], v[180:181] op_sel_hi:[1,0]
	v_pk_mul_f32 v[22:23], v[22:23], v[180:181] op_sel_hi:[1,0]
	v_pk_mul_f32 v[24:25], v[24:25], v[180:181] op_sel_hi:[1,0]
	v_pk_mul_f32 v[26:27], v[26:27], v[180:181] op_sel_hi:[1,0]
	v_pk_mul_f32 v[28:29], v[28:29], v[180:181] op_sel_hi:[1,0]
	v_pk_mul_f32 v[30:31], v[30:31], v[180:181] op_sel_hi:[1,0]
	v_pk_mul_f32 v[16:17], v[12:13], v[16:17]
	v_pk_mul_f32 v[18:19], v[14:15], v[18:19]
	v_pk_mul_f32 v[20:21], v[8:9], v[20:21]
	v_pk_mul_f32 v[22:23], v[10:11], v[22:23]
	v_pk_mul_f32 v[24:25], v[4:5], v[24:25]
	v_pk_mul_f32 v[26:27], v[6:7], v[26:27]
	v_pk_mul_f32 v[28:29], v[0:1], v[28:29]
	v_pk_mul_f32 v[30:31], v[2:3], v[30:31]
	s_waitcnt lgkmcnt(0)
	v_pk_add_f32 v[144:145], v[144:145], 1.0 op_sel_hi:[1,0]
	v_pk_add_f32 v[146:147], v[146:147], 1.0 op_sel_hi:[1,0]
	v_pk_fma_f32 v[16:17], v[144:145], v[16:17], v[160:161]
	v_pk_fma_f32 v[18:19], v[146:147], v[18:19], v[162:163]
	v_cvt_pk_f16_f32 v16, v16, v17
	v_cvt_pk_f16_f32 v17, v18, v19
	global_store_dwordx2 v183, v[16:17], s[14:15] offset:0
	v_pk_add_f32 v[148:149], v[148:149], 1.0 op_sel_hi:[1,0]
	v_pk_add_f32 v[150:151], v[150:151], 1.0 op_sel_hi:[1,0]
	v_pk_fma_f32 v[20:21], v[148:149], v[20:21], v[164:165]
	v_pk_fma_f32 v[22:23], v[150:151], v[22:23], v[166:167]
	v_cvt_pk_f16_f32 v20, v20, v21
	v_cvt_pk_f16_f32 v21, v22, v23
	global_store_dwordx2 v183, v[20:21], s[14:15] offset:512
	v_pk_add_f32 v[152:153], v[152:153], 1.0 op_sel_hi:[1,0]
	v_pk_add_f32 v[154:155], v[154:155], 1.0 op_sel_hi:[1,0]
	v_pk_fma_f32 v[24:25], v[152:153], v[24:25], v[168:169]
	v_pk_fma_f32 v[26:27], v[154:155], v[26:27], v[170:171]
	v_cvt_pk_f16_f32 v24, v24, v25
	v_cvt_pk_f16_f32 v25, v26, v27
	global_store_dwordx2 v183, v[24:25], s[14:15] offset:1024
	v_pk_add_f32 v[156:157], v[156:157], 1.0 op_sel_hi:[1,0]
	v_pk_add_f32 v[158:159], v[158:159], 1.0 op_sel_hi:[1,0]
	v_pk_fma_f32 v[28:29], v[156:157], v[28:29], v[172:173]
	v_pk_fma_f32 v[30:31], v[158:159], v[30:31], v[174:175]
	v_cvt_pk_f16_f32 v28, v28, v29
	v_cvt_pk_f16_f32 v29, v30, v31
	global_store_dwordx2 v183, v[28:29], s[14:15] offset:1536
	s_add_u32 s14, s14, 0x400000
	s_addc_u32 s15, s15, 0
	s_waitcnt vmcnt(28)
	ds_read_b128 v[144:147], v184 offset:8192
	ds_read_b128 v[148:151], v184 offset:9216
	ds_read_b128 v[152:155], v184 offset:10240
	ds_read_b128 v[156:159], v184 offset:11264
	ds_read_b128 v[160:163], v184 offset:12288
	ds_read_b128 v[164:167], v184 offset:13312
	ds_read_b128 v[168:171], v184 offset:14336
	ds_read_b128 v[172:175], v184 offset:15360
	v_mul_f32_e32 v176, v33, v33
	v_mul_f32_e32 v177, v37, v37
	v_mul_f32_e32 v178, v41, v41
	v_mul_f32_e32 v179, v45, v45
	v_fmac_f32_e32 v176, v32, v32
	v_fmac_f32_e32 v177, v36, v36
	v_fmac_f32_e32 v178, v40, v40
	v_fmac_f32_e32 v179, v44, v44
	v_fmac_f32_e32 v176, v34, v34
	v_fmac_f32_e32 v177, v38, v38
	v_fmac_f32_e32 v178, v42, v42
	v_fmac_f32_e32 v179, v46, v46
	v_fmac_f32_e32 v176, v35, v35
	v_fmac_f32_e32 v177, v39, v39
	v_fmac_f32_e32 v178, v43, v43
	v_fmac_f32_e32 v179, v47, v47
	v_add_f32_e32 v176, v177, v176
	v_add_f32_e32 v176, v178, v176
	v_add_f32_e32 v176, v179, v176
	s_nop 1
	v_add_f32_dpp v176, v176, v176 quad_perm:[1,0,3,2] row_mask:0xf bank_mask:0xf
	s_nop 1
	v_add_f32_dpp v176, v176, v176 quad_perm:[2,3,0,1] row_mask:0xf bank_mask:0xf
	s_nop 1
	v_add_f32_dpp v176, v176, v176 row_half_mirror row_mask:0xf bank_mask:0xf
	s_nop 1
	v_add_f32_dpp v176, v176, v176 row_mirror row_mask:0xf bank_mask:0xf
	s_nop 1
	v_readlane_b32 s18, v176, 0
	v_readlane_b32 s19, v176, 16
	v_readlane_b32 s20, v176, 32
	v_readlane_b32 s21, v176, 48
	s_nop 1
	v_mov_b32_e32 v177, s19
	v_mov_b32_e32 v178, s21
	v_add_f32_e32 v177, s18, v177
	v_add_f32_e32 v178, s20, v178
	v_add_f32_e32 v176, v177, v178
	v_fmamk_f32 v176, v176, 0x3a800000, v210
	v_rsq_f32_e32 v180, v176
	s_nop 0
	v_pk_mul_f32 v[32:33], v[32:33], v[180:181] op_sel_hi:[1,0]
	v_pk_mul_f32 v[34:35], v[34:35], v[180:181] op_sel_hi:[1,0]
	v_pk_mul_f32 v[36:37], v[36:37], v[180:181] op_sel_hi:[1,0]
	v_pk_mul_f32 v[38:39], v[38:39], v[180:181] op_sel_hi:[1,0]
	v_pk_mul_f32 v[40:41], v[40:41], v[180:181] op_sel_hi:[1,0]
	v_pk_mul_f32 v[42:43], v[42:43], v[180:181] op_sel_hi:[1,0]
	v_pk_mul_f32 v[44:45], v[44:45], v[180:181] op_sel_hi:[1,0]
	v_pk_mul_f32 v[46:47], v[46:47], v[180:181] op_sel_hi:[1,0]
	v_pk_mul_f32 v[32:33], v[12:13], v[32:33]
	v_pk_mul_f32 v[34:35], v[14:15], v[34:35]
	v_pk_mul_f32 v[36:37], v[8:9], v[36:37]
	v_pk_mul_f32 v[38:39], v[10:11], v[38:39]
	v_pk_mul_f32 v[40:41], v[4:5], v[40:41]
	v_pk_mul_f32 v[42:43], v[6:7], v[42:43]
	v_pk_mul_f32 v[44:45], v[0:1], v[44:45]
	v_pk_mul_f32 v[46:47], v[2:3], v[46:47]
	s_waitcnt lgkmcnt(0)
	v_pk_add_f32 v[144:145], v[144:145], 1.0 op_sel_hi:[1,0]
	v_pk_add_f32 v[146:147], v[146:147], 1.0 op_sel_hi:[1,0]
	v_pk_fma_f32 v[32:33], v[144:145], v[32:33], v[160:161]
	v_pk_fma_f32 v[34:35], v[146:147], v[34:35], v[162:163]
	v_cvt_pk_f16_f32 v32, v32, v33
	v_cvt_pk_f16_f32 v33, v34, v35
	global_store_dwordx2 v183, v[32:33], s[14:15] offset:0
	v_pk_add_f32 v[148:149], v[148:149], 1.0 op_sel_hi:[1,0]
	v_pk_add_f32 v[150:151], v[150:151], 1.0 op_sel_hi:[1,0]
	v_pk_fma_f32 v[36:37], v[148:149], v[36:37], v[164:165]
	v_pk_fma_f32 v[38:39], v[150:151], v[38:39], v[166:167]
	v_cvt_pk_f16_f32 v36, v36, v37
	v_cvt_pk_f16_f32 v37, v38, v39
	global_store_dwordx2 v183, v[36:37], s[14:15] offset:512
	v_pk_add_f32 v[152:153], v[152:153], 1.0 op_sel_hi:[1,0]
	v_pk_add_f32 v[154:155], v[154:155], 1.0 op_sel_hi:[1,0]
	v_pk_fma_f32 v[40:41], v[152:153], v[40:41], v[168:169]
	v_pk_fma_f32 v[42:43], v[154:155], v[42:43], v[170:171]
	v_cvt_pk_f16_f32 v40, v40, v41
	v_cvt_pk_f16_f32 v41, v42, v43
	global_store_dwordx2 v183, v[40:41], s[14:15] offset:1024
	v_pk_add_f32 v[156:157], v[156:157], 1.0 op_sel_hi:[1,0]
	v_pk_add_f32 v[158:159], v[158:159], 1.0 op_sel_hi:[1,0]
	v_pk_fma_f32 v[44:45], v[156:157], v[44:45], v[172:173]
	v_pk_fma_f32 v[46:47], v[158:159], v[46:47], v[174:175]
	v_cvt_pk_f16_f32 v44, v44, v45
	v_cvt_pk_f16_f32 v45, v46, v47
	global_store_dwordx2 v183, v[44:45], s[14:15] offset:1536
	s_add_u32 s14, s14, 0x400000
	s_addc_u32 s15, s15, 0
	s_waitcnt vmcnt(28)
	ds_read_b128 v[144:147], v184 offset:16384
	ds_read_b128 v[148:151], v184 offset:17408
	ds_read_b128 v[152:155], v184 offset:18432
	ds_read_b128 v[156:159], v184 offset:19456
	ds_read_b128 v[160:163], v184 offset:20480
	ds_read_b128 v[164:167], v184 offset:21504
	ds_read_b128 v[168:171], v184 offset:22528
	ds_read_b128 v[172:175], v184 offset:23552
	v_mul_f32_e32 v176, v49, v49
	v_mul_f32_e32 v177, v53, v53
	v_mul_f32_e32 v178, v57, v57
	v_mul_f32_e32 v179, v61, v61
	v_fmac_f32_e32 v176, v48, v48
	v_fmac_f32_e32 v177, v52, v52
	v_fmac_f32_e32 v178, v56, v56
	v_fmac_f32_e32 v179, v60, v60
	v_fmac_f32_e32 v176, v50, v50
	v_fmac_f32_e32 v177, v54, v54
	v_fmac_f32_e32 v178, v58, v58
	v_fmac_f32_e32 v179, v62, v62
	v_fmac_f32_e32 v176, v51, v51
	v_fmac_f32_e32 v177, v55, v55
	v_fmac_f32_e32 v178, v59, v59
	v_fmac_f32_e32 v179, v63, v63
	v_add_f32_e32 v176, v177, v176
	v_add_f32_e32 v176, v178, v176
	v_add_f32_e32 v176, v179, v176
	s_nop 1
	v_add_f32_dpp v176, v176, v176 quad_perm:[1,0,3,2] row_mask:0xf bank_mask:0xf
	s_nop 1
	v_add_f32_dpp v176, v176, v176 quad_perm:[2,3,0,1] row_mask:0xf bank_mask:0xf
	s_nop 1
	v_add_f32_dpp v176, v176, v176 row_half_mirror row_mask:0xf bank_mask:0xf
	s_nop 1
	v_add_f32_dpp v176, v176, v176 row_mirror row_mask:0xf bank_mask:0xf
	s_nop 1
	v_readlane_b32 s18, v176, 0
	v_readlane_b32 s19, v176, 16
	v_readlane_b32 s20, v176, 32
	v_readlane_b32 s21, v176, 48
	s_nop 1
	v_mov_b32_e32 v177, s19
	v_mov_b32_e32 v178, s21
	v_add_f32_e32 v177, s18, v177
	v_add_f32_e32 v178, s20, v178
	v_add_f32_e32 v176, v177, v178
	v_fmamk_f32 v176, v176, 0x3a800000, v210
	v_rsq_f32_e32 v180, v176
	s_nop 0
	v_pk_mul_f32 v[48:49], v[48:49], v[180:181] op_sel_hi:[1,0]
	v_pk_mul_f32 v[50:51], v[50:51], v[180:181] op_sel_hi:[1,0]
	v_pk_mul_f32 v[52:53], v[52:53], v[180:181] op_sel_hi:[1,0]
	v_pk_mul_f32 v[54:55], v[54:55], v[180:181] op_sel_hi:[1,0]
	v_pk_mul_f32 v[56:57], v[56:57], v[180:181] op_sel_hi:[1,0]
	v_pk_mul_f32 v[58:59], v[58:59], v[180:181] op_sel_hi:[1,0]
	v_pk_mul_f32 v[60:61], v[60:61], v[180:181] op_sel_hi:[1,0]
	v_pk_mul_f32 v[62:63], v[62:63], v[180:181] op_sel_hi:[1,0]
	v_pk_mul_f32 v[48:49], v[12:13], v[48:49]
	v_pk_mul_f32 v[50:51], v[14:15], v[50:51]
	v_pk_mul_f32 v[52:53], v[8:9], v[52:53]
	v_pk_mul_f32 v[54:55], v[10:11], v[54:55]
	v_pk_mul_f32 v[56:57], v[4:5], v[56:57]
	v_pk_mul_f32 v[58:59], v[6:7], v[58:59]
	v_pk_mul_f32 v[60:61], v[0:1], v[60:61]
	v_pk_mul_f32 v[62:63], v[2:3], v[62:63]
	s_waitcnt lgkmcnt(0)
	v_pk_add_f32 v[144:145], v[144:145], 1.0 op_sel_hi:[1,0]
	v_pk_add_f32 v[146:147], v[146:147], 1.0 op_sel_hi:[1,0]
	v_pk_fma_f32 v[48:49], v[144:145], v[48:49], v[160:161]
	v_pk_fma_f32 v[50:51], v[146:147], v[50:51], v[162:163]
	v_cvt_pk_f16_f32 v48, v48, v49
	v_cvt_pk_f16_f32 v49, v50, v51
	global_store_dwordx2 v183, v[48:49], s[14:15] offset:0
	v_pk_add_f32 v[148:149], v[148:149], 1.0 op_sel_hi:[1,0]
	v_pk_add_f32 v[150:151], v[150:151], 1.0 op_sel_hi:[1,0]
	v_pk_fma_f32 v[52:53], v[148:149], v[52:53], v[164:165]
	v_pk_fma_f32 v[54:55], v[150:151], v[54:55], v[166:167]
	v_cvt_pk_f16_f32 v52, v52, v53
	v_cvt_pk_f16_f32 v53, v54, v55
	global_store_dwordx2 v183, v[52:53], s[14:15] offset:512
	v_pk_add_f32 v[152:153], v[152:153], 1.0 op_sel_hi:[1,0]
	v_pk_add_f32 v[154:155], v[154:155], 1.0 op_sel_hi:[1,0]
	v_pk_fma_f32 v[56:57], v[152:153], v[56:57], v[168:169]
	v_pk_fma_f32 v[58:59], v[154:155], v[58:59], v[170:171]
	v_cvt_pk_f16_f32 v56, v56, v57
	v_cvt_pk_f16_f32 v57, v58, v59
	global_store_dwordx2 v183, v[56:57], s[14:15] offset:1024
	v_pk_add_f32 v[156:157], v[156:157], 1.0 op_sel_hi:[1,0]
	v_pk_add_f32 v[158:159], v[158:159], 1.0 op_sel_hi:[1,0]
	v_pk_fma_f32 v[60:61], v[156:157], v[60:61], v[172:173]
	v_pk_fma_f32 v[62:63], v[158:159], v[62:63], v[174:175]
	v_cvt_pk_f16_f32 v60, v60, v61
	v_cvt_pk_f16_f32 v61, v62, v63
	global_store_dwordx2 v183, v[60:61], s[14:15] offset:1536
	s_add_u32 s14, s14, 0x400000
	s_addc_u32 s15, s15, 0
	s_waitcnt vmcnt(28)
	ds_read_b128 v[144:147], v184 offset:24576
	ds_read_b128 v[148:151], v184 offset:25600
	ds_read_b128 v[152:155], v184 offset:26624
	ds_read_b128 v[156:159], v184 offset:27648
	ds_read_b128 v[160:163], v184 offset:28672
	ds_read_b128 v[164:167], v184 offset:29696
	ds_read_b128 v[168:171], v184 offset:30720
	ds_read_b128 v[172:175], v184 offset:31744
	v_mul_f32_e32 v176, v65, v65
	v_mul_f32_e32 v177, v69, v69
	v_mul_f32_e32 v178, v73, v73
	v_mul_f32_e32 v179, v77, v77
	v_fmac_f32_e32 v176, v64, v64
	v_fmac_f32_e32 v177, v68, v68
	v_fmac_f32_e32 v178, v72, v72
	v_fmac_f32_e32 v179, v76, v76
	v_fmac_f32_e32 v176, v66, v66
	v_fmac_f32_e32 v177, v70, v70
	v_fmac_f32_e32 v178, v74, v74
	v_fmac_f32_e32 v179, v78, v78
	v_fmac_f32_e32 v176, v67, v67
	v_fmac_f32_e32 v177, v71, v71
	v_fmac_f32_e32 v178, v75, v75
	v_fmac_f32_e32 v179, v79, v79
	v_add_f32_e32 v176, v177, v176
	v_add_f32_e32 v176, v178, v176
	v_add_f32_e32 v176, v179, v176
	s_nop 1
	v_add_f32_dpp v176, v176, v176 quad_perm:[1,0,3,2] row_mask:0xf bank_mask:0xf
	s_nop 1
	v_add_f32_dpp v176, v176, v176 quad_perm:[2,3,0,1] row_mask:0xf bank_mask:0xf
	s_nop 1
	v_add_f32_dpp v176, v176, v176 row_half_mirror row_mask:0xf bank_mask:0xf
	s_nop 1
	v_add_f32_dpp v176, v176, v176 row_mirror row_mask:0xf bank_mask:0xf
	s_nop 1
	v_readlane_b32 s18, v176, 0
	v_readlane_b32 s19, v176, 16
	v_readlane_b32 s20, v176, 32
	v_readlane_b32 s21, v176, 48
	s_nop 1
	v_mov_b32_e32 v177, s19
	v_mov_b32_e32 v178, s21
	v_add_f32_e32 v177, s18, v177
	v_add_f32_e32 v178, s20, v178
	v_add_f32_e32 v176, v177, v178
	v_fmamk_f32 v176, v176, 0x3a800000, v210
	v_rsq_f32_e32 v180, v176
	s_nop 0
	v_pk_mul_f32 v[64:65], v[64:65], v[180:181] op_sel_hi:[1,0]
	v_pk_mul_f32 v[66:67], v[66:67], v[180:181] op_sel_hi:[1,0]
	v_pk_mul_f32 v[68:69], v[68:69], v[180:181] op_sel_hi:[1,0]
	v_pk_mul_f32 v[70:71], v[70:71], v[180:181] op_sel_hi:[1,0]
	v_pk_mul_f32 v[72:73], v[72:73], v[180:181] op_sel_hi:[1,0]
	v_pk_mul_f32 v[74:75], v[74:75], v[180:181] op_sel_hi:[1,0]
	v_pk_mul_f32 v[76:77], v[76:77], v[180:181] op_sel_hi:[1,0]
	v_pk_mul_f32 v[78:79], v[78:79], v[180:181] op_sel_hi:[1,0]
	v_pk_mul_f32 v[64:65], v[12:13], v[64:65]
	v_pk_mul_f32 v[66:67], v[14:15], v[66:67]
	v_pk_mul_f32 v[68:69], v[8:9], v[68:69]
	v_pk_mul_f32 v[70:71], v[10:11], v[70:71]
	v_pk_mul_f32 v[72:73], v[4:5], v[72:73]
	v_pk_mul_f32 v[74:75], v[6:7], v[74:75]
	v_pk_mul_f32 v[76:77], v[0:1], v[76:77]
	v_pk_mul_f32 v[78:79], v[2:3], v[78:79]
	s_waitcnt lgkmcnt(0)
	v_pk_add_f32 v[144:145], v[144:145], 1.0 op_sel_hi:[1,0]
	v_pk_add_f32 v[146:147], v[146:147], 1.0 op_sel_hi:[1,0]
	v_pk_fma_f32 v[64:65], v[144:145], v[64:65], v[160:161]
	v_pk_fma_f32 v[66:67], v[146:147], v[66:67], v[162:163]
	v_cvt_pk_f16_f32 v64, v64, v65
	v_cvt_pk_f16_f32 v65, v66, v67
	global_store_dwordx2 v183, v[64:65], s[14:15] offset:0
	v_pk_add_f32 v[148:149], v[148:149], 1.0 op_sel_hi:[1,0]
	v_pk_add_f32 v[150:151], v[150:151], 1.0 op_sel_hi:[1,0]
	v_pk_fma_f32 v[68:69], v[148:149], v[68:69], v[164:165]
	v_pk_fma_f32 v[70:71], v[150:151], v[70:71], v[166:167]
	v_cvt_pk_f16_f32 v68, v68, v69
	v_cvt_pk_f16_f32 v69, v70, v71
	global_store_dwordx2 v183, v[68:69], s[14:15] offset:512
	v_pk_add_f32 v[152:153], v[152:153], 1.0 op_sel_hi:[1,0]
	v_pk_add_f32 v[154:155], v[154:155], 1.0 op_sel_hi:[1,0]
	v_pk_fma_f32 v[72:73], v[152:153], v[72:73], v[168:169]
	v_pk_fma_f32 v[74:75], v[154:155], v[74:75], v[170:171]
	v_cvt_pk_f16_f32 v72, v72, v73
	v_cvt_pk_f16_f32 v73, v74, v75
	global_store_dwordx2 v183, v[72:73], s[14:15] offset:1024
	v_pk_add_f32 v[156:157], v[156:157], 1.0 op_sel_hi:[1,0]
	v_pk_add_f32 v[158:159], v[158:159], 1.0 op_sel_hi:[1,0]
	v_pk_fma_f32 v[76:77], v[156:157], v[76:77], v[172:173]
	v_pk_fma_f32 v[78:79], v[158:159], v[78:79], v[174:175]
	v_cvt_pk_f16_f32 v76, v76, v77
	v_cvt_pk_f16_f32 v77, v78, v79
	global_store_dwordx2 v183, v[76:77], s[14:15] offset:1536
	s_add_u32 s14, s14, 0x400000
	s_addc_u32 s15, s15, 0
	s_waitcnt vmcnt(28)
	ds_read_b128 v[144:147], v184 offset:32768
	ds_read_b128 v[148:151], v184 offset:33792
	ds_read_b128 v[152:155], v184 offset:34816
	ds_read_b128 v[156:159], v184 offset:35840
	ds_read_b128 v[160:163], v184 offset:36864
	ds_read_b128 v[164:167], v184 offset:37888
	ds_read_b128 v[168:171], v184 offset:38912
	ds_read_b128 v[172:175], v184 offset:39936
	v_mul_f32_e32 v176, v81, v81
	v_mul_f32_e32 v177, v85, v85
	v_mul_f32_e32 v178, v89, v89
	v_mul_f32_e32 v179, v93, v93
	v_fmac_f32_e32 v176, v80, v80
	v_fmac_f32_e32 v177, v84, v84
	v_fmac_f32_e32 v178, v88, v88
	v_fmac_f32_e32 v179, v92, v92
	v_fmac_f32_e32 v176, v82, v82
	v_fmac_f32_e32 v177, v86, v86
	v_fmac_f32_e32 v178, v90, v90
	v_fmac_f32_e32 v179, v94, v94
	v_fmac_f32_e32 v176, v83, v83
	v_fmac_f32_e32 v177, v87, v87
	v_fmac_f32_e32 v178, v91, v91
	v_fmac_f32_e32 v179, v95, v95
	v_add_f32_e32 v176, v177, v176
	v_add_f32_e32 v176, v178, v176
	v_add_f32_e32 v176, v179, v176
	s_nop 1
	v_add_f32_dpp v176, v176, v176 quad_perm:[1,0,3,2] row_mask:0xf bank_mask:0xf
	s_nop 1
	v_add_f32_dpp v176, v176, v176 quad_perm:[2,3,0,1] row_mask:0xf bank_mask:0xf
	s_nop 1
	v_add_f32_dpp v176, v176, v176 row_half_mirror row_mask:0xf bank_mask:0xf
	s_nop 1
	v_add_f32_dpp v176, v176, v176 row_mirror row_mask:0xf bank_mask:0xf
	s_nop 1
	v_readlane_b32 s18, v176, 0
	v_readlane_b32 s19, v176, 16
	v_readlane_b32 s20, v176, 32
	v_readlane_b32 s21, v176, 48
	s_nop 1
	v_mov_b32_e32 v177, s19
	v_mov_b32_e32 v178, s21
	v_add_f32_e32 v177, s18, v177
	v_add_f32_e32 v178, s20, v178
	v_add_f32_e32 v176, v177, v178
	v_fmamk_f32 v176, v176, 0x3a800000, v210
	v_rsq_f32_e32 v180, v176
	s_nop 0
	v_pk_mul_f32 v[80:81], v[80:81], v[180:181] op_sel_hi:[1,0]
	v_pk_mul_f32 v[82:83], v[82:83], v[180:181] op_sel_hi:[1,0]
	v_pk_mul_f32 v[84:85], v[84:85], v[180:181] op_sel_hi:[1,0]
	v_pk_mul_f32 v[86:87], v[86:87], v[180:181] op_sel_hi:[1,0]
	v_pk_mul_f32 v[88:89], v[88:89], v[180:181] op_sel_hi:[1,0]
	v_pk_mul_f32 v[90:91], v[90:91], v[180:181] op_sel_hi:[1,0]
	v_pk_mul_f32 v[92:93], v[92:93], v[180:181] op_sel_hi:[1,0]
	v_pk_mul_f32 v[94:95], v[94:95], v[180:181] op_sel_hi:[1,0]
	v_pk_mul_f32 v[80:81], v[12:13], v[80:81]
	v_pk_mul_f32 v[82:83], v[14:15], v[82:83]
	v_pk_mul_f32 v[84:85], v[8:9], v[84:85]
	v_pk_mul_f32 v[86:87], v[10:11], v[86:87]
	v_pk_mul_f32 v[88:89], v[4:5], v[88:89]
	v_pk_mul_f32 v[90:91], v[6:7], v[90:91]
	v_pk_mul_f32 v[92:93], v[0:1], v[92:93]
	v_pk_mul_f32 v[94:95], v[2:3], v[94:95]
	s_waitcnt lgkmcnt(0)
	v_pk_add_f32 v[144:145], v[144:145], 1.0 op_sel_hi:[1,0]
	v_pk_add_f32 v[146:147], v[146:147], 1.0 op_sel_hi:[1,0]
	v_pk_fma_f32 v[80:81], v[144:145], v[80:81], v[160:161]
	v_pk_fma_f32 v[82:83], v[146:147], v[82:83], v[162:163]
	v_cvt_pk_f16_f32 v80, v80, v81
	v_cvt_pk_f16_f32 v81, v82, v83
	global_store_dwordx2 v183, v[80:81], s[14:15] offset:0
	v_pk_add_f32 v[148:149], v[148:149], 1.0 op_sel_hi:[1,0]
	v_pk_add_f32 v[150:151], v[150:151], 1.0 op_sel_hi:[1,0]
	v_pk_fma_f32 v[84:85], v[148:149], v[84:85], v[164:165]
	v_pk_fma_f32 v[86:87], v[150:151], v[86:87], v[166:167]
	v_cvt_pk_f16_f32 v84, v84, v85
	v_cvt_pk_f16_f32 v85, v86, v87
	global_store_dwordx2 v183, v[84:85], s[14:15] offset:512
	v_pk_add_f32 v[152:153], v[152:153], 1.0 op_sel_hi:[1,0]
	v_pk_add_f32 v[154:155], v[154:155], 1.0 op_sel_hi:[1,0]
	v_pk_fma_f32 v[88:89], v[152:153], v[88:89], v[168:169]
	v_pk_fma_f32 v[90:91], v[154:155], v[90:91], v[170:171]
	v_cvt_pk_f16_f32 v88, v88, v89
	v_cvt_pk_f16_f32 v89, v90, v91
	global_store_dwordx2 v183, v[88:89], s[14:15] offset:1024
	v_pk_add_f32 v[156:157], v[156:157], 1.0 op_sel_hi:[1,0]
	v_pk_add_f32 v[158:159], v[158:159], 1.0 op_sel_hi:[1,0]
	v_pk_fma_f32 v[92:93], v[156:157], v[92:93], v[172:173]
	v_pk_fma_f32 v[94:95], v[158:159], v[94:95], v[174:175]
	v_cvt_pk_f16_f32 v92, v92, v93
	v_cvt_pk_f16_f32 v93, v94, v95
	global_store_dwordx2 v183, v[92:93], s[14:15] offset:1536
	s_add_u32 s14, s14, 0x400000
	s_addc_u32 s15, s15, 0
	s_waitcnt vmcnt(28)
	ds_read_b128 v[144:147], v184 offset:40960
	ds_read_b128 v[148:151], v184 offset:41984
	ds_read_b128 v[152:155], v184 offset:43008
	ds_read_b128 v[156:159], v184 offset:44032
	ds_read_b128 v[160:163], v184 offset:45056
	ds_read_b128 v[164:167], v184 offset:46080
	ds_read_b128 v[168:171], v184 offset:47104
	ds_read_b128 v[172:175], v184 offset:48128
	v_mul_f32_e32 v176, v97, v97
	v_mul_f32_e32 v177, v101, v101
	v_mul_f32_e32 v178, v105, v105
	v_mul_f32_e32 v179, v109, v109
	v_fmac_f32_e32 v176, v96, v96
	v_fmac_f32_e32 v177, v100, v100
	v_fmac_f32_e32 v178, v104, v104
	v_fmac_f32_e32 v179, v108, v108
	v_fmac_f32_e32 v176, v98, v98
	v_fmac_f32_e32 v177, v102, v102
	v_fmac_f32_e32 v178, v106, v106
	v_fmac_f32_e32 v179, v110, v110
	v_fmac_f32_e32 v176, v99, v99
	v_fmac_f32_e32 v177, v103, v103
	v_fmac_f32_e32 v178, v107, v107
	v_fmac_f32_e32 v179, v111, v111
	v_add_f32_e32 v176, v177, v176
	v_add_f32_e32 v176, v178, v176
	v_add_f32_e32 v176, v179, v176
	s_nop 1
	v_add_f32_dpp v176, v176, v176 quad_perm:[1,0,3,2] row_mask:0xf bank_mask:0xf
	s_nop 1
	v_add_f32_dpp v176, v176, v176 quad_perm:[2,3,0,1] row_mask:0xf bank_mask:0xf
	s_nop 1
	v_add_f32_dpp v176, v176, v176 row_half_mirror row_mask:0xf bank_mask:0xf
	s_nop 1
	v_add_f32_dpp v176, v176, v176 row_mirror row_mask:0xf bank_mask:0xf
	s_nop 1
	v_readlane_b32 s18, v176, 0
	v_readlane_b32 s19, v176, 16
	v_readlane_b32 s20, v176, 32
	v_readlane_b32 s21, v176, 48
	s_nop 1
	v_mov_b32_e32 v177, s19
	v_mov_b32_e32 v178, s21
	v_add_f32_e32 v177, s18, v177
	v_add_f32_e32 v178, s20, v178
	v_add_f32_e32 v176, v177, v178
	v_fmamk_f32 v176, v176, 0x3a800000, v210
	v_rsq_f32_e32 v180, v176
	s_nop 0
	v_pk_mul_f32 v[96:97], v[96:97], v[180:181] op_sel_hi:[1,0]
	v_pk_mul_f32 v[98:99], v[98:99], v[180:181] op_sel_hi:[1,0]
	v_pk_mul_f32 v[100:101], v[100:101], v[180:181] op_sel_hi:[1,0]
	v_pk_mul_f32 v[102:103], v[102:103], v[180:181] op_sel_hi:[1,0]
	v_pk_mul_f32 v[104:105], v[104:105], v[180:181] op_sel_hi:[1,0]
	v_pk_mul_f32 v[106:107], v[106:107], v[180:181] op_sel_hi:[1,0]
	v_pk_mul_f32 v[108:109], v[108:109], v[180:181] op_sel_hi:[1,0]
	v_pk_mul_f32 v[110:111], v[110:111], v[180:181] op_sel_hi:[1,0]
	v_pk_mul_f32 v[96:97], v[12:13], v[96:97]
	v_pk_mul_f32 v[98:99], v[14:15], v[98:99]
	v_pk_mul_f32 v[100:101], v[8:9], v[100:101]
	v_pk_mul_f32 v[102:103], v[10:11], v[102:103]
	v_pk_mul_f32 v[104:105], v[4:5], v[104:105]
	v_pk_mul_f32 v[106:107], v[6:7], v[106:107]
	v_pk_mul_f32 v[108:109], v[0:1], v[108:109]
	v_pk_mul_f32 v[110:111], v[2:3], v[110:111]
	s_waitcnt lgkmcnt(0)
	v_pk_add_f32 v[144:145], v[144:145], 1.0 op_sel_hi:[1,0]
	v_pk_add_f32 v[146:147], v[146:147], 1.0 op_sel_hi:[1,0]
	v_pk_fma_f32 v[96:97], v[144:145], v[96:97], v[160:161]
	v_pk_fma_f32 v[98:99], v[146:147], v[98:99], v[162:163]
	v_cvt_pk_f16_f32 v96, v96, v97
	v_cvt_pk_f16_f32 v97, v98, v99
	global_store_dwordx2 v183, v[96:97], s[14:15] offset:0
	v_pk_add_f32 v[148:149], v[148:149], 1.0 op_sel_hi:[1,0]
	v_pk_add_f32 v[150:151], v[150:151], 1.0 op_sel_hi:[1,0]
	v_pk_fma_f32 v[100:101], v[148:149], v[100:101], v[164:165]
	v_pk_fma_f32 v[102:103], v[150:151], v[102:103], v[166:167]
	v_cvt_pk_f16_f32 v100, v100, v101
	v_cvt_pk_f16_f32 v101, v102, v103
	global_store_dwordx2 v183, v[100:101], s[14:15] offset:512
	v_pk_add_f32 v[152:153], v[152:153], 1.0 op_sel_hi:[1,0]
	v_pk_add_f32 v[154:155], v[154:155], 1.0 op_sel_hi:[1,0]
	v_pk_fma_f32 v[104:105], v[152:153], v[104:105], v[168:169]
	v_pk_fma_f32 v[106:107], v[154:155], v[106:107], v[170:171]
	v_cvt_pk_f16_f32 v104, v104, v105
	v_cvt_pk_f16_f32 v105, v106, v107
	global_store_dwordx2 v183, v[104:105], s[14:15] offset:1024
	v_pk_add_f32 v[156:157], v[156:157], 1.0 op_sel_hi:[1,0]
	v_pk_add_f32 v[158:159], v[158:159], 1.0 op_sel_hi:[1,0]
	v_pk_fma_f32 v[108:109], v[156:157], v[108:109], v[172:173]
	v_pk_fma_f32 v[110:111], v[158:159], v[110:111], v[174:175]
	v_cvt_pk_f16_f32 v108, v108, v109
	v_cvt_pk_f16_f32 v109, v110, v111
	global_store_dwordx2 v183, v[108:109], s[14:15] offset:1536
	s_add_u32 s14, s14, 0x400000
	s_addc_u32 s15, s15, 0
	s_waitcnt vmcnt(28)
	ds_read_b128 v[144:147], v184 offset:49152
	ds_read_b128 v[148:151], v184 offset:50176
	ds_read_b128 v[152:155], v184 offset:51200
	ds_read_b128 v[156:159], v184 offset:52224
	ds_read_b128 v[160:163], v184 offset:53248
	ds_read_b128 v[164:167], v184 offset:54272
	ds_read_b128 v[168:171], v184 offset:55296
	ds_read_b128 v[172:175], v184 offset:56320
	v_mul_f32_e32 v176, v113, v113
	v_mul_f32_e32 v177, v117, v117
	v_mul_f32_e32 v178, v121, v121
	v_mul_f32_e32 v179, v125, v125
	v_fmac_f32_e32 v176, v112, v112
	v_fmac_f32_e32 v177, v116, v116
	v_fmac_f32_e32 v178, v120, v120
	v_fmac_f32_e32 v179, v124, v124
	v_fmac_f32_e32 v176, v114, v114
	v_fmac_f32_e32 v177, v118, v118
	v_fmac_f32_e32 v178, v122, v122
	v_fmac_f32_e32 v179, v126, v126
	v_fmac_f32_e32 v176, v115, v115
	v_fmac_f32_e32 v177, v119, v119
	v_fmac_f32_e32 v178, v123, v123
	v_fmac_f32_e32 v179, v127, v127
	v_add_f32_e32 v176, v177, v176
	v_add_f32_e32 v176, v178, v176
	v_add_f32_e32 v176, v179, v176
	s_nop 1
	v_add_f32_dpp v176, v176, v176 quad_perm:[1,0,3,2] row_mask:0xf bank_mask:0xf
	s_nop 1
	v_add_f32_dpp v176, v176, v176 quad_perm:[2,3,0,1] row_mask:0xf bank_mask:0xf
	s_nop 1
	v_add_f32_dpp v176, v176, v176 row_half_mirror row_mask:0xf bank_mask:0xf
	s_nop 1
	v_add_f32_dpp v176, v176, v176 row_mirror row_mask:0xf bank_mask:0xf
	s_nop 1
	v_readlane_b32 s18, v176, 0
	v_readlane_b32 s19, v176, 16
	v_readlane_b32 s20, v176, 32
	v_readlane_b32 s21, v176, 48
	s_nop 1
	v_mov_b32_e32 v177, s19
	v_mov_b32_e32 v178, s21
	v_add_f32_e32 v177, s18, v177
	v_add_f32_e32 v178, s20, v178
	v_add_f32_e32 v176, v177, v178
	v_fmamk_f32 v176, v176, 0x3a800000, v210
	v_rsq_f32_e32 v180, v176
	s_nop 0
	v_pk_mul_f32 v[112:113], v[112:113], v[180:181] op_sel_hi:[1,0]
	v_pk_mul_f32 v[114:115], v[114:115], v[180:181] op_sel_hi:[1,0]
	v_pk_mul_f32 v[116:117], v[116:117], v[180:181] op_sel_hi:[1,0]
	v_pk_mul_f32 v[118:119], v[118:119], v[180:181] op_sel_hi:[1,0]
	v_pk_mul_f32 v[120:121], v[120:121], v[180:181] op_sel_hi:[1,0]
	v_pk_mul_f32 v[122:123], v[122:123], v[180:181] op_sel_hi:[1,0]
	v_pk_mul_f32 v[124:125], v[124:125], v[180:181] op_sel_hi:[1,0]
	v_pk_mul_f32 v[126:127], v[126:127], v[180:181] op_sel_hi:[1,0]
	v_pk_mul_f32 v[112:113], v[12:13], v[112:113]
	v_pk_mul_f32 v[114:115], v[14:15], v[114:115]
	v_pk_mul_f32 v[116:117], v[8:9], v[116:117]
	v_pk_mul_f32 v[118:119], v[10:11], v[118:119]
	v_pk_mul_f32 v[120:121], v[4:5], v[120:121]
	v_pk_mul_f32 v[122:123], v[6:7], v[122:123]
	v_pk_mul_f32 v[124:125], v[0:1], v[124:125]
	v_pk_mul_f32 v[126:127], v[2:3], v[126:127]
	s_waitcnt lgkmcnt(0)
	v_pk_add_f32 v[144:145], v[144:145], 1.0 op_sel_hi:[1,0]
	v_pk_add_f32 v[146:147], v[146:147], 1.0 op_sel_hi:[1,0]
	v_pk_fma_f32 v[112:113], v[144:145], v[112:113], v[160:161]
	v_pk_fma_f32 v[114:115], v[146:147], v[114:115], v[162:163]
	v_cvt_pk_f16_f32 v112, v112, v113
	v_cvt_pk_f16_f32 v113, v114, v115
	global_store_dwordx2 v183, v[112:113], s[14:15] offset:0
	v_pk_add_f32 v[148:149], v[148:149], 1.0 op_sel_hi:[1,0]
	v_pk_add_f32 v[150:151], v[150:151], 1.0 op_sel_hi:[1,0]
	v_pk_fma_f32 v[116:117], v[148:149], v[116:117], v[164:165]
	v_pk_fma_f32 v[118:119], v[150:151], v[118:119], v[166:167]
	v_cvt_pk_f16_f32 v116, v116, v117
	v_cvt_pk_f16_f32 v117, v118, v119
	global_store_dwordx2 v183, v[116:117], s[14:15] offset:512
	v_pk_add_f32 v[152:153], v[152:153], 1.0 op_sel_hi:[1,0]
	v_pk_add_f32 v[154:155], v[154:155], 1.0 op_sel_hi:[1,0]
	v_pk_fma_f32 v[120:121], v[152:153], v[120:121], v[168:169]
	v_pk_fma_f32 v[122:123], v[154:155], v[122:123], v[170:171]
	v_cvt_pk_f16_f32 v120, v120, v121
	v_cvt_pk_f16_f32 v121, v122, v123
	global_store_dwordx2 v183, v[120:121], s[14:15] offset:1024
	v_pk_add_f32 v[156:157], v[156:157], 1.0 op_sel_hi:[1,0]
	v_pk_add_f32 v[158:159], v[158:159], 1.0 op_sel_hi:[1,0]
	v_pk_fma_f32 v[124:125], v[156:157], v[124:125], v[172:173]
	v_pk_fma_f32 v[126:127], v[158:159], v[126:127], v[174:175]
	v_cvt_pk_f16_f32 v124, v124, v125
	v_cvt_pk_f16_f32 v125, v126, v127
	global_store_dwordx2 v183, v[124:125], s[14:15] offset:1536
	s_add_u32 s14, s14, 0x400000
	s_addc_u32 s15, s15, 0
	s_waitcnt vmcnt(28)
	ds_read_b128 v[144:147], v184 offset:57344
	ds_read_b128 v[148:151], v184 offset:58368
	ds_read_b128 v[152:155], v184 offset:59392
	ds_read_b128 v[156:159], v184 offset:60416
	ds_read_b128 v[160:163], v184 offset:61440
	ds_read_b128 v[164:167], v184 offset:62464
	ds_read_b128 v[168:171], v184 offset:63488
	ds_read_b128 v[172:175], v184 offset:64512
	v_mul_f32_e32 v176, v129, v129
	v_mul_f32_e32 v177, v133, v133
	v_mul_f32_e32 v178, v137, v137
	v_mul_f32_e32 v179, v141, v141
	v_fmac_f32_e32 v176, v128, v128
	v_fmac_f32_e32 v177, v132, v132
	v_fmac_f32_e32 v178, v136, v136
	v_fmac_f32_e32 v179, v140, v140
	v_fmac_f32_e32 v176, v130, v130
	v_fmac_f32_e32 v177, v134, v134
	v_fmac_f32_e32 v178, v138, v138
	v_fmac_f32_e32 v179, v142, v142
	v_fmac_f32_e32 v176, v131, v131
	v_fmac_f32_e32 v177, v135, v135
	v_fmac_f32_e32 v178, v139, v139
	v_fmac_f32_e32 v179, v143, v143
	v_add_f32_e32 v176, v177, v176
	v_add_f32_e32 v176, v178, v176
	v_add_f32_e32 v176, v179, v176
	s_nop 1
	v_add_f32_dpp v176, v176, v176 quad_perm:[1,0,3,2] row_mask:0xf bank_mask:0xf
	s_nop 1
	v_add_f32_dpp v176, v176, v176 quad_perm:[2,3,0,1] row_mask:0xf bank_mask:0xf
	s_nop 1
	v_add_f32_dpp v176, v176, v176 row_half_mirror row_mask:0xf bank_mask:0xf
	s_nop 1
	v_add_f32_dpp v176, v176, v176 row_mirror row_mask:0xf bank_mask:0xf
	s_nop 1
	v_readlane_b32 s18, v176, 0
	v_readlane_b32 s19, v176, 16
	v_readlane_b32 s20, v176, 32
	v_readlane_b32 s21, v176, 48
	s_nop 1
	v_mov_b32_e32 v177, s19
	v_mov_b32_e32 v178, s21
	v_add_f32_e32 v177, s18, v177
	v_add_f32_e32 v178, s20, v178
	v_add_f32_e32 v176, v177, v178
	v_fmamk_f32 v176, v176, 0x3a800000, v210
	v_rsq_f32_e32 v180, v176
	s_nop 0
	v_pk_mul_f32 v[128:129], v[128:129], v[180:181] op_sel_hi:[1,0]
	v_pk_mul_f32 v[130:131], v[130:131], v[180:181] op_sel_hi:[1,0]
	v_pk_mul_f32 v[132:133], v[132:133], v[180:181] op_sel_hi:[1,0]
	v_pk_mul_f32 v[134:135], v[134:135], v[180:181] op_sel_hi:[1,0]
	v_pk_mul_f32 v[136:137], v[136:137], v[180:181] op_sel_hi:[1,0]
	v_pk_mul_f32 v[138:139], v[138:139], v[180:181] op_sel_hi:[1,0]
	v_pk_mul_f32 v[140:141], v[140:141], v[180:181] op_sel_hi:[1,0]
	v_pk_mul_f32 v[142:143], v[142:143], v[180:181] op_sel_hi:[1,0]
	v_pk_mul_f32 v[128:129], v[12:13], v[128:129]
	v_pk_mul_f32 v[130:131], v[14:15], v[130:131]
	v_pk_mul_f32 v[132:133], v[8:9], v[132:133]
	v_pk_mul_f32 v[134:135], v[10:11], v[134:135]
	v_pk_mul_f32 v[136:137], v[4:5], v[136:137]
	v_pk_mul_f32 v[138:139], v[6:7], v[138:139]
	v_pk_mul_f32 v[140:141], v[0:1], v[140:141]
	v_pk_mul_f32 v[142:143], v[2:3], v[142:143]
	s_waitcnt lgkmcnt(0)
	v_pk_add_f32 v[144:145], v[144:145], 1.0 op_sel_hi:[1,0]
	v_pk_add_f32 v[146:147], v[146:147], 1.0 op_sel_hi:[1,0]
	v_pk_fma_f32 v[128:129], v[144:145], v[128:129], v[160:161]
	v_pk_fma_f32 v[130:131], v[146:147], v[130:131], v[162:163]
	v_cvt_pk_f16_f32 v128, v128, v129
	v_cvt_pk_f16_f32 v129, v130, v131
	global_store_dwordx2 v183, v[128:129], s[14:15] offset:0
	v_pk_add_f32 v[148:149], v[148:149], 1.0 op_sel_hi:[1,0]
	v_pk_add_f32 v[150:151], v[150:151], 1.0 op_sel_hi:[1,0]
	v_pk_fma_f32 v[132:133], v[148:149], v[132:133], v[164:165]
	v_pk_fma_f32 v[134:135], v[150:151], v[134:135], v[166:167]
	v_cvt_pk_f16_f32 v132, v132, v133
	v_cvt_pk_f16_f32 v133, v134, v135
	global_store_dwordx2 v183, v[132:133], s[14:15] offset:512
	v_pk_add_f32 v[152:153], v[152:153], 1.0 op_sel_hi:[1,0]
	v_pk_add_f32 v[154:155], v[154:155], 1.0 op_sel_hi:[1,0]
	v_pk_fma_f32 v[136:137], v[152:153], v[136:137], v[168:169]
	v_pk_fma_f32 v[138:139], v[154:155], v[138:139], v[170:171]
	v_cvt_pk_f16_f32 v136, v136, v137
	v_cvt_pk_f16_f32 v137, v138, v139
	global_store_dwordx2 v183, v[136:137], s[14:15] offset:1024
	v_pk_add_f32 v[156:157], v[156:157], 1.0 op_sel_hi:[1,0]
	v_pk_add_f32 v[158:159], v[158:159], 1.0 op_sel_hi:[1,0]
	v_pk_fma_f32 v[140:141], v[156:157], v[140:141], v[172:173]
	v_pk_fma_f32 v[142:143], v[158:159], v[142:143], v[174:175]
	v_cvt_pk_f16_f32 v140, v140, v141
	v_cvt_pk_f16_f32 v141, v142, v143
	global_store_dwordx2 v183, v[140:141], s[14:15] offset:1536
	v_mov_b32_e32 v72, v192

.LBB0_1693:
	v_readlane_b32 s22, v253, 33
	v_readlane_b32 s16, v254, 22
	v_readlane_b32 s17, v254, 23
	v_lshlrev_b32_e32 v182, 4, v192
	v_lshlrev_b32_e32 v183, 3, v192
	s_and_b32 s23, s22, 3
	s_lshl_b32 s23, s23, 10
	s_bitcmp1_b32 s22, 2
	s_mov_b32 s18, 0x4000
	s_cselect_b32 s18, 0x3000, s18
	s_add_u32 s23, s23, s18
	s_add_u32 s16, s16, s23
	s_addc_u32 s17, s17, 0
	s_and_b32 s18, s22, 7
	s_lshl_b32 s18, s18, 10
	v_add_u32_e32 v185, s18, v182
	v_add_u32_e32 v185, 0x4000, v185
	v_add_u32_e32 v184, 0x4000, v182
	v_readfirstlane_b32 s12, v76
	v_readfirstlane_b32 s13, v77
	s_lshl_b32 s23, s22, 12
	s_add_u32 s12, s12, s23
	s_addc_u32 s13, s13, 0
	s_lshl_b32 s23, s22, 11
	s_add_u32 s14, s0, s23
	s_addc_u32 s15, s1, 0
	s_add_u32 s14, s14, 0x3200000
	s_addc_u32 s15, s15, 0
	global_load_dwordx4 v[144:147], v182, s[16:17]
	s_add_u32 s16, s16, 0x6000
	s_addc_u32 s17, s17, 0
	global_load_dwordx4 v[148:151], v182, s[16:17]
	s_add_u32 s16, s16, 0x6000
	s_addc_u32 s17, s17, 0
	global_load_dwordx4 v[152:155], v182, s[16:17]
	s_add_u32 s16, s16, 0x6000
	s_addc_u32 s17, s17, 0
	global_load_dwordx4 v[156:159], v182, s[16:17]
	s_add_u32 s16, s16, 0x6000
	s_addc_u32 s17, s17, 0
	global_load_dwordx4 v[160:163], v182, s[16:17]
	s_add_u32 s16, s16, 0x6000
	s_addc_u32 s17, s17, 0
	global_load_dwordx4 v[164:167], v182, s[16:17]
	s_add_u32 s16, s16, 0x6000
	s_addc_u32 s17, s17, 0
	global_load_dwordx4 v[168:171], v182, s[16:17]
	s_add_u32 s16, s16, 0x6000
	s_addc_u32 s17, s17, 0
	global_load_dwordx4 v[172:175], v182, s[16:17]
	global_load_dwordx4 v[16:19], v182, s[12:13] offset:0
	global_load_dwordx4 v[20:23], v182, s[12:13] offset:1024
	global_load_dwordx4 v[24:27], v182, s[12:13] offset:2048
	global_load_dwordx4 v[28:31], v182, s[12:13] offset:3072
	s_add_u32 s12, s12, 0x800000
	s_addc_u32 s13, s13, 0
	global_load_dwordx4 v[32:35], v182, s[12:13] offset:0
	global_load_dwordx4 v[36:39], v182, s[12:13] offset:1024
	global_load_dwordx4 v[40:43], v182, s[12:13] offset:2048
	global_load_dwordx4 v[44:47], v182, s[12:13] offset:3072
	s_add_u32 s12, s12, 0x800000
	s_addc_u32 s13, s13, 0
	global_load_dwordx4 v[48:51], v182, s[12:13] offset:0
	global_load_dwordx4 v[52:55], v182, s[12:13] offset:1024
	global_load_dwordx4 v[56:59], v182, s[12:13] offset:2048
	global_load_dwordx4 v[60:63], v182, s[12:13] offset:3072
	s_add_u32 s12, s12, 0x800000
	s_addc_u32 s13, s13, 0
	global_load_dwordx4 v[64:67], v182, s[12:13] offset:0
	global_load_dwordx4 v[68:71], v182, s[12:13] offset:1024
	global_load_dwordx4 v[72:75], v182, s[12:13] offset:2048
	global_load_dwordx4 v[76:79], v182, s[12:13] offset:3072
	s_add_u32 s12, s12, 0x800000
	s_addc_u32 s13, s13, 0
	global_load_dwordx4 v[80:83], v182, s[12:13] offset:0
	global_load_dwordx4 v[84:87], v182, s[12:13] offset:1024
	global_load_dwordx4 v[88:91], v182, s[12:13] offset:2048
	global_load_dwordx4 v[92:95], v182, s[12:13] offset:3072
	s_add_u32 s12, s12, 0x800000
	s_addc_u32 s13, s13, 0
	global_load_dwordx4 v[96:99], v182, s[12:13] offset:0
	global_load_dwordx4 v[100:103], v182, s[12:13] offset:1024
	global_load_dwordx4 v[104:107], v182, s[12:13] offset:2048
	global_load_dwordx4 v[108:111], v182, s[12:13] offset:3072
	s_add_u32 s12, s12, 0x800000
	s_addc_u32 s13, s13, 0
	global_load_dwordx4 v[112:115], v182, s[12:13] offset:0
	global_load_dwordx4 v[116:119], v182, s[12:13] offset:1024
	global_load_dwordx4 v[120:123], v182, s[12:13] offset:2048
	global_load_dwordx4 v[124:127], v182, s[12:13] offset:3072
	s_add_u32 s12, s12, 0x800000
	s_addc_u32 s13, s13, 0
	global_load_dwordx4 v[128:131], v182, s[12:13] offset:0
	global_load_dwordx4 v[132:135], v182, s[12:13] offset:1024
	global_load_dwordx4 v[136:139], v182, s[12:13] offset:2048
	global_load_dwordx4 v[140:143], v182, s[12:13] offset:3072
	s_waitcnt vmcnt(32)
	ds_write_b128 v185, v[144:147] offset:0
	ds_write_b128 v185, v[148:151] offset:8192
	ds_write_b128 v185, v[152:155] offset:16384
	ds_write_b128 v185, v[156:159] offset:24576
	ds_write_b128 v185, v[160:163] offset:32768
	ds_write_b128 v185, v[164:167] offset:40960
	ds_write_b128 v185, v[168:171] offset:49152
	ds_write_b128 v185, v[172:175] offset:57344
	s_waitcnt lgkmcnt(0)
	s_barrier
	s_waitcnt vmcnt(28)
	ds_read_b128 v[144:147], v184 offset:0
	ds_read_b128 v[148:151], v184 offset:1024
	ds_read_b128 v[152:155], v184 offset:2048
	ds_read_b128 v[156:159], v184 offset:3072
	ds_read_b128 v[160:163], v184 offset:4096
	ds_read_b128 v[164:167], v184 offset:5120
	ds_read_b128 v[168:171], v184 offset:6144
	ds_read_b128 v[172:175], v184 offset:7168
	v_mul_f32_e32 v176, v17, v17
	v_mul_f32_e32 v177, v21, v21
	v_mul_f32_e32 v178, v25, v25
	v_mul_f32_e32 v179, v29, v29
	v_fmac_f32_e32 v176, v16, v16
	v_fmac_f32_e32 v177, v20, v20
	v_fmac_f32_e32 v178, v24, v24
	v_fmac_f32_e32 v179, v28, v28
	v_fmac_f32_e32 v176, v18, v18
	v_fmac_f32_e32 v177, v22, v22
	v_fmac_f32_e32 v178, v26, v26
	v_fmac_f32_e32 v179, v30, v30
	v_fmac_f32_e32 v176, v19, v19
	v_fmac_f32_e32 v177, v23, v23
	v_fmac_f32_e32 v178, v27, v27
	v_fmac_f32_e32 v179, v31, v31
	v_add_f32_e32 v176, v177, v176
	v_add_f32_e32 v176, v178, v176
	v_add_f32_e32 v176, v179, v176
	s_nop 1
	v_add_f32_dpp v176, v176, v176 quad_perm:[1,0,3,2] row_mask:0xf bank_mask:0xf
	s_nop 1
	v_add_f32_dpp v176, v176, v176 quad_perm:[2,3,0,1] row_mask:0xf bank_mask:0xf
	s_nop 1
	v_add_f32_dpp v176, v176, v176 row_half_mirror row_mask:0xf bank_mask:0xf
	s_nop 1
	v_add_f32_dpp v176, v176, v176 row_mirror row_mask:0xf bank_mask:0xf
	s_nop 1
	v_readlane_b32 s18, v176, 0
	v_readlane_b32 s19, v176, 16
	v_readlane_b32 s20, v176, 32
	v_readlane_b32 s21, v176, 48
	s_nop 1
	v_mov_b32_e32 v177, s19
	v_mov_b32_e32 v178, s21
	v_add_f32_e32 v177, s18, v177
	v_add_f32_e32 v178, s20, v178
	v_add_f32_e32 v176, v177, v178
	v_fmamk_f32 v176, v176, 0x3a800000, v210
	v_rsq_f32_e32 v180, v176
	s_nop 0
	v_pk_mul_f32 v[16:17], v[16:17], v[180:181] op_sel_hi:[1,0]
	v_pk_mul_f32 v[18:19], v[18:19], v[180:181] op_sel_hi:[1,0]
	v_pk_mul_f32 v[20:21], v[20:21], v[180:181] op_sel_hi:[1,0]
	v_pk_mul_f32 v[22:23], v[22:23], v[180:181] op_sel_hi:[1,0]
	v_pk_mul_f32 v[24:25], v[24:25], v[180:181] op_sel_hi:[1,0]
	v_pk_mul_f32 v[26:27], v[26:27], v[180:181] op_sel_hi:[1,0]
	v_pk_mul_f32 v[28:29], v[28:29], v[180:181] op_sel_hi:[1,0]
	v_pk_mul_f32 v[30:31], v[30:31], v[180:181] op_sel_hi:[1,0]
	v_pk_mul_f32 v[16:17], v[12:13], v[16:17]
	v_pk_mul_f32 v[18:19], v[14:15], v[18:19]
	v_pk_mul_f32 v[20:21], v[8:9], v[20:21]
	v_pk_mul_f32 v[22:23], v[10:11], v[22:23]
	v_pk_mul_f32 v[24:25], v[4:5], v[24:25]
	v_pk_mul_f32 v[26:27], v[6:7], v[26:27]
	v_pk_mul_f32 v[28:29], v[0:1], v[28:29]
	v_pk_mul_f32 v[30:31], v[2:3], v[30:31]
	s_waitcnt lgkmcnt(0)
	v_pk_add_f32 v[144:145], v[144:145], 1.0 op_sel_hi:[1,0]
	v_pk_add_f32 v[146:147], v[146:147], 1.0 op_sel_hi:[1,0]
	v_pk_fma_f32 v[16:17], v[144:145], v[16:17], v[160:161]
	v_pk_fma_f32 v[18:19], v[146:147], v[18:19], v[162:163]
	v_cvt_pk_f16_f32 v16, v16, v17
	v_cvt_pk_f16_f32 v17, v18, v19
	global_store_dwordx2 v183, v[16:17], s[14:15] offset:0
	v_pk_add_f32 v[148:149], v[148:149], 1.0 op_sel_hi:[1,0]
	v_pk_add_f32 v[150:151], v[150:151], 1.0 op_sel_hi:[1,0]
	v_pk_fma_f32 v[20:21], v[148:149], v[20:21], v[164:165]
	v_pk_fma_f32 v[22:23], v[150:151], v[22:23], v[166:167]
	v_cvt_pk_f16_f32 v20, v20, v21
	v_cvt_pk_f16_f32 v21, v22, v23
	global_store_dwordx2 v183, v[20:21], s[14:15] offset:512
	v_pk_add_f32 v[152:153], v[152:153], 1.0 op_sel_hi:[1,0]
	v_pk_add_f32 v[154:155], v[154:155], 1.0 op_sel_hi:[1,0]
	v_pk_fma_f32 v[24:25], v[152:153], v[24:25], v[168:169]
	v_pk_fma_f32 v[26:27], v[154:155], v[26:27], v[170:171]
	v_cvt_pk_f16_f32 v24, v24, v25
	v_cvt_pk_f16_f32 v25, v26, v27
	global_store_dwordx2 v183, v[24:25], s[14:15] offset:1024
	v_pk_add_f32 v[156:157], v[156:157], 1.0 op_sel_hi:[1,0]
	v_pk_add_f32 v[158:159], v[158:159], 1.0 op_sel_hi:[1,0]
	v_pk_fma_f32 v[28:29], v[156:157], v[28:29], v[172:173]
	v_pk_fma_f32 v[30:31], v[158:159], v[30:31], v[174:175]
	v_cvt_pk_f16_f32 v28, v28, v29
	v_cvt_pk_f16_f32 v29, v30, v31
	global_store_dwordx2 v183, v[28:29], s[14:15] offset:1536
	s_add_u32 s14, s14, 0x400000
	s_addc_u32 s15, s15, 0
	s_waitcnt vmcnt(28)
	ds_read_b128 v[144:147], v184 offset:8192
	ds_read_b128 v[148:151], v184 offset:9216
	ds_read_b128 v[152:155], v184 offset:10240
	ds_read_b128 v[156:159], v184 offset:11264
	ds_read_b128 v[160:163], v184 offset:12288
	ds_read_b128 v[164:167], v184 offset:13312
	ds_read_b128 v[168:171], v184 offset:14336
	ds_read_b128 v[172:175], v184 offset:15360
	v_mul_f32_e32 v176, v33, v33
	v_mul_f32_e32 v177, v37, v37
	v_mul_f32_e32 v178, v41, v41
	v_mul_f32_e32 v179, v45, v45
	v_fmac_f32_e32 v176, v32, v32
	v_fmac_f32_e32 v177, v36, v36
	v_fmac_f32_e32 v178, v40, v40
	v_fmac_f32_e32 v179, v44, v44
	v_fmac_f32_e32 v176, v34, v34
	v_fmac_f32_e32 v177, v38, v38
	v_fmac_f32_e32 v178, v42, v42
	v_fmac_f32_e32 v179, v46, v46
	v_fmac_f32_e32 v176, v35, v35
	v_fmac_f32_e32 v177, v39, v39
	v_fmac_f32_e32 v178, v43, v43
	v_fmac_f32_e32 v179, v47, v47
	v_add_f32_e32 v176, v177, v176
	v_add_f32_e32 v176, v178, v176
	v_add_f32_e32 v176, v179, v176
	s_nop 1
	v_add_f32_dpp v176, v176, v176 quad_perm:[1,0,3,2] row_mask:0xf bank_mask:0xf
	s_nop 1
	v_add_f32_dpp v176, v176, v176 quad_perm:[2,3,0,1] row_mask:0xf bank_mask:0xf
	s_nop 1
	v_add_f32_dpp v176, v176, v176 row_half_mirror row_mask:0xf bank_mask:0xf
	s_nop 1
	v_add_f32_dpp v176, v176, v176 row_mirror row_mask:0xf bank_mask:0xf
	s_nop 1
	v_readlane_b32 s18, v176, 0
	v_readlane_b32 s19, v176, 16
	v_readlane_b32 s20, v176, 32
	v_readlane_b32 s21, v176, 48
	s_nop 1
	v_mov_b32_e32 v177, s19
	v_mov_b32_e32 v178, s21
	v_add_f32_e32 v177, s18, v177
	v_add_f32_e32 v178, s20, v178
	v_add_f32_e32 v176, v177, v178
	v_fmamk_f32 v176, v176, 0x3a800000, v210
	v_rsq_f32_e32 v180, v176
	s_nop 0
	v_pk_mul_f32 v[32:33], v[32:33], v[180:181] op_sel_hi:[1,0]
	v_pk_mul_f32 v[34:35], v[34:35], v[180:181] op_sel_hi:[1,0]
	v_pk_mul_f32 v[36:37], v[36:37], v[180:181] op_sel_hi:[1,0]
	v_pk_mul_f32 v[38:39], v[38:39], v[180:181] op_sel_hi:[1,0]
	v_pk_mul_f32 v[40:41], v[40:41], v[180:181] op_sel_hi:[1,0]
	v_pk_mul_f32 v[42:43], v[42:43], v[180:181] op_sel_hi:[1,0]
	v_pk_mul_f32 v[44:45], v[44:45], v[180:181] op_sel_hi:[1,0]
	v_pk_mul_f32 v[46:47], v[46:47], v[180:181] op_sel_hi:[1,0]
	v_pk_mul_f32 v[32:33], v[12:13], v[32:33]
	v_pk_mul_f32 v[34:35], v[14:15], v[34:35]
	v_pk_mul_f32 v[36:37], v[8:9], v[36:37]
	v_pk_mul_f32 v[38:39], v[10:11], v[38:39]
	v_pk_mul_f32 v[40:41], v[4:5], v[40:41]
	v_pk_mul_f32 v[42:43], v[6:7], v[42:43]
	v_pk_mul_f32 v[44:45], v[0:1], v[44:45]
	v_pk_mul_f32 v[46:47], v[2:3], v[46:47]
	s_waitcnt lgkmcnt(0)
	v_pk_add_f32 v[144:145], v[144:145], 1.0 op_sel_hi:[1,0]
	v_pk_add_f32 v[146:147], v[146:147], 1.0 op_sel_hi:[1,0]
	v_pk_fma_f32 v[32:33], v[144:145], v[32:33], v[160:161]
	v_pk_fma_f32 v[34:35], v[146:147], v[34:35], v[162:163]
	v_cvt_pk_f16_f32 v32, v32, v33
	v_cvt_pk_f16_f32 v33, v34, v35
	global_store_dwordx2 v183, v[32:33], s[14:15] offset:0
	v_pk_add_f32 v[148:149], v[148:149], 1.0 op_sel_hi:[1,0]
	v_pk_add_f32 v[150:151], v[150:151], 1.0 op_sel_hi:[1,0]
	v_pk_fma_f32 v[36:37], v[148:149], v[36:37], v[164:165]
	v_pk_fma_f32 v[38:39], v[150:151], v[38:39], v[166:167]
	v_cvt_pk_f16_f32 v36, v36, v37
	v_cvt_pk_f16_f32 v37, v38, v39
	global_store_dwordx2 v183, v[36:37], s[14:15] offset:512
	v_pk_add_f32 v[152:153], v[152:153], 1.0 op_sel_hi:[1,0]
	v_pk_add_f32 v[154:155], v[154:155], 1.0 op_sel_hi:[1,0]
	v_pk_fma_f32 v[40:41], v[152:153], v[40:41], v[168:169]
	v_pk_fma_f32 v[42:43], v[154:155], v[42:43], v[170:171]
	v_cvt_pk_f16_f32 v40, v40, v41
	v_cvt_pk_f16_f32 v41, v42, v43
	global_store_dwordx2 v183, v[40:41], s[14:15] offset:1024
	v_pk_add_f32 v[156:157], v[156:157], 1.0 op_sel_hi:[1,0]
	v_pk_add_f32 v[158:159], v[158:159], 1.0 op_sel_hi:[1,0]
	v_pk_fma_f32 v[44:45], v[156:157], v[44:45], v[172:173]
	v_pk_fma_f32 v[46:47], v[158:159], v[46:47], v[174:175]
	v_cvt_pk_f16_f32 v44, v44, v45
	v_cvt_pk_f16_f32 v45, v46, v47
	global_store_dwordx2 v183, v[44:45], s[14:15] offset:1536
	s_add_u32 s14, s14, 0x400000
	s_addc_u32 s15, s15, 0
	s_waitcnt vmcnt(28)
	ds_read_b128 v[144:147], v184 offset:16384
	ds_read_b128 v[148:151], v184 offset:17408
	ds_read_b128 v[152:155], v184 offset:18432
	ds_read_b128 v[156:159], v184 offset:19456
	ds_read_b128 v[160:163], v184 offset:20480
	ds_read_b128 v[164:167], v184 offset:21504
	ds_read_b128 v[168:171], v184 offset:22528
	ds_read_b128 v[172:175], v184 offset:23552
	v_mul_f32_e32 v176, v49, v49
	v_mul_f32_e32 v177, v53, v53
	v_mul_f32_e32 v178, v57, v57
	v_mul_f32_e32 v179, v61, v61
	v_fmac_f32_e32 v176, v48, v48
	v_fmac_f32_e32 v177, v52, v52
	v_fmac_f32_e32 v178, v56, v56
	v_fmac_f32_e32 v179, v60, v60
	v_fmac_f32_e32 v176, v50, v50
	v_fmac_f32_e32 v177, v54, v54
	v_fmac_f32_e32 v178, v58, v58
	v_fmac_f32_e32 v179, v62, v62
	v_fmac_f32_e32 v176, v51, v51
	v_fmac_f32_e32 v177, v55, v55
	v_fmac_f32_e32 v178, v59, v59
	v_fmac_f32_e32 v179, v63, v63
	v_add_f32_e32 v176, v177, v176
	v_add_f32_e32 v176, v178, v176
	v_add_f32_e32 v176, v179, v176
	s_nop 1
	v_add_f32_dpp v176, v176, v176 quad_perm:[1,0,3,2] row_mask:0xf bank_mask:0xf
	s_nop 1
	v_add_f32_dpp v176, v176, v176 quad_perm:[2,3,0,1] row_mask:0xf bank_mask:0xf
	s_nop 1
	v_add_f32_dpp v176, v176, v176 row_half_mirror row_mask:0xf bank_mask:0xf
	s_nop 1
	v_add_f32_dpp v176, v176, v176 row_mirror row_mask:0xf bank_mask:0xf
	s_nop 1
	v_readlane_b32 s18, v176, 0
	v_readlane_b32 s19, v176, 16
	v_readlane_b32 s20, v176, 32
	v_readlane_b32 s21, v176, 48
	s_nop 1
	v_mov_b32_e32 v177, s19
	v_mov_b32_e32 v178, s21
	v_add_f32_e32 v177, s18, v177
	v_add_f32_e32 v178, s20, v178
	v_add_f32_e32 v176, v177, v178
	v_fmamk_f32 v176, v176, 0x3a800000, v210
	v_rsq_f32_e32 v180, v176
	s_nop 0
	v_pk_mul_f32 v[48:49], v[48:49], v[180:181] op_sel_hi:[1,0]
	v_pk_mul_f32 v[50:51], v[50:51], v[180:181] op_sel_hi:[1,0]
	v_pk_mul_f32 v[52:53], v[52:53], v[180:181] op_sel_hi:[1,0]
	v_pk_mul_f32 v[54:55], v[54:55], v[180:181] op_sel_hi:[1,0]
	v_pk_mul_f32 v[56:57], v[56:57], v[180:181] op_sel_hi:[1,0]
	v_pk_mul_f32 v[58:59], v[58:59], v[180:181] op_sel_hi:[1,0]
	v_pk_mul_f32 v[60:61], v[60:61], v[180:181] op_sel_hi:[1,0]
	v_pk_mul_f32 v[62:63], v[62:63], v[180:181] op_sel_hi:[1,0]
	v_pk_mul_f32 v[48:49], v[12:13], v[48:49]
	v_pk_mul_f32 v[50:51], v[14:15], v[50:51]
	v_pk_mul_f32 v[52:53], v[8:9], v[52:53]
	v_pk_mul_f32 v[54:55], v[10:11], v[54:55]
	v_pk_mul_f32 v[56:57], v[4:5], v[56:57]
	v_pk_mul_f32 v[58:59], v[6:7], v[58:59]
	v_pk_mul_f32 v[60:61], v[0:1], v[60:61]
	v_pk_mul_f32 v[62:63], v[2:3], v[62:63]
	s_waitcnt lgkmcnt(0)
	v_pk_add_f32 v[144:145], v[144:145], 1.0 op_sel_hi:[1,0]
	v_pk_add_f32 v[146:147], v[146:147], 1.0 op_sel_hi:[1,0]
	v_pk_fma_f32 v[48:49], v[144:145], v[48:49], v[160:161]
	v_pk_fma_f32 v[50:51], v[146:147], v[50:51], v[162:163]
	v_cvt_pk_f16_f32 v48, v48, v49
	v_cvt_pk_f16_f32 v49, v50, v51
	global_store_dwordx2 v183, v[48:49], s[14:15] offset:0
	v_pk_add_f32 v[148:149], v[148:149], 1.0 op_sel_hi:[1,0]
	v_pk_add_f32 v[150:151], v[150:151], 1.0 op_sel_hi:[1,0]
	v_pk_fma_f32 v[52:53], v[148:149], v[52:53], v[164:165]
	v_pk_fma_f32 v[54:55], v[150:151], v[54:55], v[166:167]
	v_cvt_pk_f16_f32 v52, v52, v53
	v_cvt_pk_f16_f32 v53, v54, v55
	global_store_dwordx2 v183, v[52:53], s[14:15] offset:512
	v_pk_add_f32 v[152:153], v[152:153], 1.0 op_sel_hi:[1,0]
	v_pk_add_f32 v[154:155], v[154:155], 1.0 op_sel_hi:[1,0]
	v_pk_fma_f32 v[56:57], v[152:153], v[56:57], v[168:169]
	v_pk_fma_f32 v[58:59], v[154:155], v[58:59], v[170:171]
	v_cvt_pk_f16_f32 v56, v56, v57
	v_cvt_pk_f16_f32 v57, v58, v59
	global_store_dwordx2 v183, v[56:57], s[14:15] offset:1024
	v_pk_add_f32 v[156:157], v[156:157], 1.0 op_sel_hi:[1,0]
	v_pk_add_f32 v[158:159], v[158:159], 1.0 op_sel_hi:[1,0]
	v_pk_fma_f32 v[60:61], v[156:157], v[60:61], v[172:173]
	v_pk_fma_f32 v[62:63], v[158:159], v[62:63], v[174:175]
	v_cvt_pk_f16_f32 v60, v60, v61
	v_cvt_pk_f16_f32 v61, v62, v63
	global_store_dwordx2 v183, v[60:61], s[14:15] offset:1536
	s_add_u32 s14, s14, 0x400000
	s_addc_u32 s15, s15, 0
	s_waitcnt vmcnt(28)
	ds_read_b128 v[144:147], v184 offset:24576
	ds_read_b128 v[148:151], v184 offset:25600
	ds_read_b128 v[152:155], v184 offset:26624
	ds_read_b128 v[156:159], v184 offset:27648
	ds_read_b128 v[160:163], v184 offset:28672
	ds_read_b128 v[164:167], v184 offset:29696
	ds_read_b128 v[168:171], v184 offset:30720
	ds_read_b128 v[172:175], v184 offset:31744
	v_mul_f32_e32 v176, v65, v65
	v_mul_f32_e32 v177, v69, v69
	v_mul_f32_e32 v178, v73, v73
	v_mul_f32_e32 v179, v77, v77
	v_fmac_f32_e32 v176, v64, v64
	v_fmac_f32_e32 v177, v68, v68
	v_fmac_f32_e32 v178, v72, v72
	v_fmac_f32_e32 v179, v76, v76
	v_fmac_f32_e32 v176, v66, v66
	v_fmac_f32_e32 v177, v70, v70
	v_fmac_f32_e32 v178, v74, v74
	v_fmac_f32_e32 v179, v78, v78
	v_fmac_f32_e32 v176, v67, v67
	v_fmac_f32_e32 v177, v71, v71
	v_fmac_f32_e32 v178, v75, v75
	v_fmac_f32_e32 v179, v79, v79
	v_add_f32_e32 v176, v177, v176
	v_add_f32_e32 v176, v178, v176
	v_add_f32_e32 v176, v179, v176
	s_nop 1
	v_add_f32_dpp v176, v176, v176 quad_perm:[1,0,3,2] row_mask:0xf bank_mask:0xf
	s_nop 1
	v_add_f32_dpp v176, v176, v176 quad_perm:[2,3,0,1] row_mask:0xf bank_mask:0xf
	s_nop 1
	v_add_f32_dpp v176, v176, v176 row_half_mirror row_mask:0xf bank_mask:0xf
	s_nop 1
	v_add_f32_dpp v176, v176, v176 row_mirror row_mask:0xf bank_mask:0xf
	s_nop 1
	v_readlane_b32 s18, v176, 0
	v_readlane_b32 s19, v176, 16
	v_readlane_b32 s20, v176, 32
	v_readlane_b32 s21, v176, 48
	s_nop 1
	v_mov_b32_e32 v177, s19
	v_mov_b32_e32 v178, s21
	v_add_f32_e32 v177, s18, v177
	v_add_f32_e32 v178, s20, v178
	v_add_f32_e32 v176, v177, v178
	v_fmamk_f32 v176, v176, 0x3a800000, v210
	v_rsq_f32_e32 v180, v176
	s_nop 0
	v_pk_mul_f32 v[64:65], v[64:65], v[180:181] op_sel_hi:[1,0]
	v_pk_mul_f32 v[66:67], v[66:67], v[180:181] op_sel_hi:[1,0]
	v_pk_mul_f32 v[68:69], v[68:69], v[180:181] op_sel_hi:[1,0]
	v_pk_mul_f32 v[70:71], v[70:71], v[180:181] op_sel_hi:[1,0]
	v_pk_mul_f32 v[72:73], v[72:73], v[180:181] op_sel_hi:[1,0]
	v_pk_mul_f32 v[74:75], v[74:75], v[180:181] op_sel_hi:[1,0]
	v_pk_mul_f32 v[76:77], v[76:77], v[180:181] op_sel_hi:[1,0]
	v_pk_mul_f32 v[78:79], v[78:79], v[180:181] op_sel_hi:[1,0]
	v_pk_mul_f32 v[64:65], v[12:13], v[64:65]
	v_pk_mul_f32 v[66:67], v[14:15], v[66:67]
	v_pk_mul_f32 v[68:69], v[8:9], v[68:69]
	v_pk_mul_f32 v[70:71], v[10:11], v[70:71]
	v_pk_mul_f32 v[72:73], v[4:5], v[72:73]
	v_pk_mul_f32 v[74:75], v[6:7], v[74:75]
	v_pk_mul_f32 v[76:77], v[0:1], v[76:77]
	v_pk_mul_f32 v[78:79], v[2:3], v[78:79]
	s_waitcnt lgkmcnt(0)
	v_pk_add_f32 v[144:145], v[144:145], 1.0 op_sel_hi:[1,0]
	v_pk_add_f32 v[146:147], v[146:147], 1.0 op_sel_hi:[1,0]
	v_pk_fma_f32 v[64:65], v[144:145], v[64:65], v[160:161]
	v_pk_fma_f32 v[66:67], v[146:147], v[66:67], v[162:163]
	v_cvt_pk_f16_f32 v64, v64, v65
	v_cvt_pk_f16_f32 v65, v66, v67
	global_store_dwordx2 v183, v[64:65], s[14:15] offset:0
	v_pk_add_f32 v[148:149], v[148:149], 1.0 op_sel_hi:[1,0]
	v_pk_add_f32 v[150:151], v[150:151], 1.0 op_sel_hi:[1,0]
	v_pk_fma_f32 v[68:69], v[148:149], v[68:69], v[164:165]
	v_pk_fma_f32 v[70:71], v[150:151], v[70:71], v[166:167]
	v_cvt_pk_f16_f32 v68, v68, v69
	v_cvt_pk_f16_f32 v69, v70, v71
	global_store_dwordx2 v183, v[68:69], s[14:15] offset:512
	v_pk_add_f32 v[152:153], v[152:153], 1.0 op_sel_hi:[1,0]
	v_pk_add_f32 v[154:155], v[154:155], 1.0 op_sel_hi:[1,0]
	v_pk_fma_f32 v[72:73], v[152:153], v[72:73], v[168:169]
	v_pk_fma_f32 v[74:75], v[154:155], v[74:75], v[170:171]
	v_cvt_pk_f16_f32 v72, v72, v73
	v_cvt_pk_f16_f32 v73, v74, v75
	global_store_dwordx2 v183, v[72:73], s[14:15] offset:1024
	v_pk_add_f32 v[156:157], v[156:157], 1.0 op_sel_hi:[1,0]
	v_pk_add_f32 v[158:159], v[158:159], 1.0 op_sel_hi:[1,0]
	v_pk_fma_f32 v[76:77], v[156:157], v[76:77], v[172:173]
	v_pk_fma_f32 v[78:79], v[158:159], v[78:79], v[174:175]
	v_cvt_pk_f16_f32 v76, v76, v77
	v_cvt_pk_f16_f32 v77, v78, v79
	global_store_dwordx2 v183, v[76:77], s[14:15] offset:1536
	s_add_u32 s14, s14, 0x400000
	s_addc_u32 s15, s15, 0
	s_waitcnt vmcnt(28)
	ds_read_b128 v[144:147], v184 offset:32768
	ds_read_b128 v[148:151], v184 offset:33792
	ds_read_b128 v[152:155], v184 offset:34816
	ds_read_b128 v[156:159], v184 offset:35840
	ds_read_b128 v[160:163], v184 offset:36864
	ds_read_b128 v[164:167], v184 offset:37888
	ds_read_b128 v[168:171], v184 offset:38912
	ds_read_b128 v[172:175], v184 offset:39936
	v_mul_f32_e32 v176, v81, v81
	v_mul_f32_e32 v177, v85, v85
	v_mul_f32_e32 v178, v89, v89
	v_mul_f32_e32 v179, v93, v93
	v_fmac_f32_e32 v176, v80, v80
	v_fmac_f32_e32 v177, v84, v84
	v_fmac_f32_e32 v178, v88, v88
	v_fmac_f32_e32 v179, v92, v92
	v_fmac_f32_e32 v176, v82, v82
	v_fmac_f32_e32 v177, v86, v86
	v_fmac_f32_e32 v178, v90, v90
	v_fmac_f32_e32 v179, v94, v94
	v_fmac_f32_e32 v176, v83, v83
	v_fmac_f32_e32 v177, v87, v87
	v_fmac_f32_e32 v178, v91, v91
	v_fmac_f32_e32 v179, v95, v95
	v_add_f32_e32 v176, v177, v176
	v_add_f32_e32 v176, v178, v176
	v_add_f32_e32 v176, v179, v176
	s_nop 1
	v_add_f32_dpp v176, v176, v176 quad_perm:[1,0,3,2] row_mask:0xf bank_mask:0xf
	s_nop 1
	v_add_f32_dpp v176, v176, v176 quad_perm:[2,3,0,1] row_mask:0xf bank_mask:0xf
	s_nop 1
	v_add_f32_dpp v176, v176, v176 row_half_mirror row_mask:0xf bank_mask:0xf
	s_nop 1
	v_add_f32_dpp v176, v176, v176 row_mirror row_mask:0xf bank_mask:0xf
	s_nop 1
	v_readlane_b32 s18, v176, 0
	v_readlane_b32 s19, v176, 16
	v_readlane_b32 s20, v176, 32
	v_readlane_b32 s21, v176, 48
	s_nop 1
	v_mov_b32_e32 v177, s19
	v_mov_b32_e32 v178, s21
	v_add_f32_e32 v177, s18, v177
	v_add_f32_e32 v178, s20, v178
	v_add_f32_e32 v176, v177, v178
	v_fmamk_f32 v176, v176, 0x3a800000, v210
	v_rsq_f32_e32 v180, v176
	s_nop 0
	v_pk_mul_f32 v[80:81], v[80:81], v[180:181] op_sel_hi:[1,0]
	v_pk_mul_f32 v[82:83], v[82:83], v[180:181] op_sel_hi:[1,0]
	v_pk_mul_f32 v[84:85], v[84:85], v[180:181] op_sel_hi:[1,0]
	v_pk_mul_f32 v[86:87], v[86:87], v[180:181] op_sel_hi:[1,0]
	v_pk_mul_f32 v[88:89], v[88:89], v[180:181] op_sel_hi:[1,0]
	v_pk_mul_f32 v[90:91], v[90:91], v[180:181] op_sel_hi:[1,0]
	v_pk_mul_f32 v[92:93], v[92:93], v[180:181] op_sel_hi:[1,0]
	v_pk_mul_f32 v[94:95], v[94:95], v[180:181] op_sel_hi:[1,0]
	v_pk_mul_f32 v[80:81], v[12:13], v[80:81]
	v_pk_mul_f32 v[82:83], v[14:15], v[82:83]
	v_pk_mul_f32 v[84:85], v[8:9], v[84:85]
	v_pk_mul_f32 v[86:87], v[10:11], v[86:87]
	v_pk_mul_f32 v[88:89], v[4:5], v[88:89]
	v_pk_mul_f32 v[90:91], v[6:7], v[90:91]
	v_pk_mul_f32 v[92:93], v[0:1], v[92:93]
	v_pk_mul_f32 v[94:95], v[2:3], v[94:95]
	s_waitcnt lgkmcnt(0)
	v_pk_add_f32 v[144:145], v[144:145], 1.0 op_sel_hi:[1,0]
	v_pk_add_f32 v[146:147], v[146:147], 1.0 op_sel_hi:[1,0]
	v_pk_fma_f32 v[80:81], v[144:145], v[80:81], v[160:161]
	v_pk_fma_f32 v[82:83], v[146:147], v[82:83], v[162:163]
	v_cvt_pk_f16_f32 v80, v80, v81
	v_cvt_pk_f16_f32 v81, v82, v83
	global_store_dwordx2 v183, v[80:81], s[14:15] offset:0
	v_pk_add_f32 v[148:149], v[148:149], 1.0 op_sel_hi:[1,0]
	v_pk_add_f32 v[150:151], v[150:151], 1.0 op_sel_hi:[1,0]
	v_pk_fma_f32 v[84:85], v[148:149], v[84:85], v[164:165]
	v_pk_fma_f32 v[86:87], v[150:151], v[86:87], v[166:167]
	v_cvt_pk_f16_f32 v84, v84, v85
	v_cvt_pk_f16_f32 v85, v86, v87
	global_store_dwordx2 v183, v[84:85], s[14:15] offset:512
	v_pk_add_f32 v[152:153], v[152:153], 1.0 op_sel_hi:[1,0]
	v_pk_add_f32 v[154:155], v[154:155], 1.0 op_sel_hi:[1,0]
	v_pk_fma_f32 v[88:89], v[152:153], v[88:89], v[168:169]
	v_pk_fma_f32 v[90:91], v[154:155], v[90:91], v[170:171]
	v_cvt_pk_f16_f32 v88, v88, v89
	v_cvt_pk_f16_f32 v89, v90, v91
	global_store_dwordx2 v183, v[88:89], s[14:15] offset:1024
	v_pk_add_f32 v[156:157], v[156:157], 1.0 op_sel_hi:[1,0]
	v_pk_add_f32 v[158:159], v[158:159], 1.0 op_sel_hi:[1,0]
	v_pk_fma_f32 v[92:93], v[156:157], v[92:93], v[172:173]
	v_pk_fma_f32 v[94:95], v[158:159], v[94:95], v[174:175]
	v_cvt_pk_f16_f32 v92, v92, v93
	v_cvt_pk_f16_f32 v93, v94, v95
	global_store_dwordx2 v183, v[92:93], s[14:15] offset:1536
	s_add_u32 s14, s14, 0x400000
	s_addc_u32 s15, s15, 0
	s_waitcnt vmcnt(28)
	ds_read_b128 v[144:147], v184 offset:40960
	ds_read_b128 v[148:151], v184 offset:41984
	ds_read_b128 v[152:155], v184 offset:43008
	ds_read_b128 v[156:159], v184 offset:44032
	ds_read_b128 v[160:163], v184 offset:45056
	ds_read_b128 v[164:167], v184 offset:46080
	ds_read_b128 v[168:171], v184 offset:47104
	ds_read_b128 v[172:175], v184 offset:48128
	v_mul_f32_e32 v176, v97, v97
	v_mul_f32_e32 v177, v101, v101
	v_mul_f32_e32 v178, v105, v105
	v_mul_f32_e32 v179, v109, v109
	v_fmac_f32_e32 v176, v96, v96
	v_fmac_f32_e32 v177, v100, v100
	v_fmac_f32_e32 v178, v104, v104
	v_fmac_f32_e32 v179, v108, v108
	v_fmac_f32_e32 v176, v98, v98
	v_fmac_f32_e32 v177, v102, v102
	v_fmac_f32_e32 v178, v106, v106
	v_fmac_f32_e32 v179, v110, v110
	v_fmac_f32_e32 v176, v99, v99
	v_fmac_f32_e32 v177, v103, v103
	v_fmac_f32_e32 v178, v107, v107
	v_fmac_f32_e32 v179, v111, v111
	v_add_f32_e32 v176, v177, v176
	v_add_f32_e32 v176, v178, v176
	v_add_f32_e32 v176, v179, v176
	s_nop 1
	v_add_f32_dpp v176, v176, v176 quad_perm:[1,0,3,2] row_mask:0xf bank_mask:0xf
	s_nop 1
	v_add_f32_dpp v176, v176, v176 quad_perm:[2,3,0,1] row_mask:0xf bank_mask:0xf
	s_nop 1
	v_add_f32_dpp v176, v176, v176 row_half_mirror row_mask:0xf bank_mask:0xf
	s_nop 1
	v_add_f32_dpp v176, v176, v176 row_mirror row_mask:0xf bank_mask:0xf
	s_nop 1
	v_readlane_b32 s18, v176, 0
	v_readlane_b32 s19, v176, 16
	v_readlane_b32 s20, v176, 32
	v_readlane_b32 s21, v176, 48
	s_nop 1
	v_mov_b32_e32 v177, s19
	v_mov_b32_e32 v178, s21
	v_add_f32_e32 v177, s18, v177
	v_add_f32_e32 v178, s20, v178
	v_add_f32_e32 v176, v177, v178
	v_fmamk_f32 v176, v176, 0x3a800000, v210
	v_rsq_f32_e32 v180, v176
	s_nop 0
	v_pk_mul_f32 v[96:97], v[96:97], v[180:181] op_sel_hi:[1,0]
	v_pk_mul_f32 v[98:99], v[98:99], v[180:181] op_sel_hi:[1,0]
	v_pk_mul_f32 v[100:101], v[100:101], v[180:181] op_sel_hi:[1,0]
	v_pk_mul_f32 v[102:103], v[102:103], v[180:181] op_sel_hi:[1,0]
	v_pk_mul_f32 v[104:105], v[104:105], v[180:181] op_sel_hi:[1,0]
	v_pk_mul_f32 v[106:107], v[106:107], v[180:181] op_sel_hi:[1,0]
	v_pk_mul_f32 v[108:109], v[108:109], v[180:181] op_sel_hi:[1,0]
	v_pk_mul_f32 v[110:111], v[110:111], v[180:181] op_sel_hi:[1,0]
	v_pk_mul_f32 v[96:97], v[12:13], v[96:97]
	v_pk_mul_f32 v[98:99], v[14:15], v[98:99]
	v_pk_mul_f32 v[100:101], v[8:9], v[100:101]
	v_pk_mul_f32 v[102:103], v[10:11], v[102:103]
	v_pk_mul_f32 v[104:105], v[4:5], v[104:105]
	v_pk_mul_f32 v[106:107], v[6:7], v[106:107]
	v_pk_mul_f32 v[108:109], v[0:1], v[108:109]
	v_pk_mul_f32 v[110:111], v[2:3], v[110:111]
	s_waitcnt lgkmcnt(0)
	v_pk_add_f32 v[144:145], v[144:145], 1.0 op_sel_hi:[1,0]
	v_pk_add_f32 v[146:147], v[146:147], 1.0 op_sel_hi:[1,0]
	v_pk_fma_f32 v[96:97], v[144:145], v[96:97], v[160:161]
	v_pk_fma_f32 v[98:99], v[146:147], v[98:99], v[162:163]
	v_cvt_pk_f16_f32 v96, v96, v97
	v_cvt_pk_f16_f32 v97, v98, v99
	global_store_dwordx2 v183, v[96:97], s[14:15] offset:0
	v_pk_add_f32 v[148:149], v[148:149], 1.0 op_sel_hi:[1,0]
	v_pk_add_f32 v[150:151], v[150:151], 1.0 op_sel_hi:[1,0]
	v_pk_fma_f32 v[100:101], v[148:149], v[100:101], v[164:165]
	v_pk_fma_f32 v[102:103], v[150:151], v[102:103], v[166:167]
	v_cvt_pk_f16_f32 v100, v100, v101
	v_cvt_pk_f16_f32 v101, v102, v103
	global_store_dwordx2 v183, v[100:101], s[14:15] offset:512
	v_pk_add_f32 v[152:153], v[152:153], 1.0 op_sel_hi:[1,0]
	v_pk_add_f32 v[154:155], v[154:155], 1.0 op_sel_hi:[1,0]
	v_pk_fma_f32 v[104:105], v[152:153], v[104:105], v[168:169]
	v_pk_fma_f32 v[106:107], v[154:155], v[106:107], v[170:171]
	v_cvt_pk_f16_f32 v104, v104, v105
	v_cvt_pk_f16_f32 v105, v106, v107
	global_store_dwordx2 v183, v[104:105], s[14:15] offset:1024
	v_pk_add_f32 v[156:157], v[156:157], 1.0 op_sel_hi:[1,0]
	v_pk_add_f32 v[158:159], v[158:159], 1.0 op_sel_hi:[1,0]
	v_pk_fma_f32 v[108:109], v[156:157], v[108:109], v[172:173]
	v_pk_fma_f32 v[110:111], v[158:159], v[110:111], v[174:175]
	v_cvt_pk_f16_f32 v108, v108, v109
	v_cvt_pk_f16_f32 v109, v110, v111
	global_store_dwordx2 v183, v[108:109], s[14:15] offset:1536
	s_add_u32 s14, s14, 0x400000
	s_addc_u32 s15, s15, 0
	s_waitcnt vmcnt(28)
	ds_read_b128 v[144:147], v184 offset:49152
	ds_read_b128 v[148:151], v184 offset:50176
	ds_read_b128 v[152:155], v184 offset:51200
	ds_read_b128 v[156:159], v184 offset:52224
	ds_read_b128 v[160:163], v184 offset:53248
	ds_read_b128 v[164:167], v184 offset:54272
	ds_read_b128 v[168:171], v184 offset:55296
	ds_read_b128 v[172:175], v184 offset:56320
	v_mul_f32_e32 v176, v113, v113
	v_mul_f32_e32 v177, v117, v117
	v_mul_f32_e32 v178, v121, v121
	v_mul_f32_e32 v179, v125, v125
	v_fmac_f32_e32 v176, v112, v112
	v_fmac_f32_e32 v177, v116, v116
	v_fmac_f32_e32 v178, v120, v120
	v_fmac_f32_e32 v179, v124, v124
	v_fmac_f32_e32 v176, v114, v114
	v_fmac_f32_e32 v177, v118, v118
	v_fmac_f32_e32 v178, v122, v122
	v_fmac_f32_e32 v179, v126, v126
	v_fmac_f32_e32 v176, v115, v115
	v_fmac_f32_e32 v177, v119, v119
	v_fmac_f32_e32 v178, v123, v123
	v_fmac_f32_e32 v179, v127, v127
	v_add_f32_e32 v176, v177, v176
	v_add_f32_e32 v176, v178, v176
	v_add_f32_e32 v176, v179, v176
	s_nop 1
	v_add_f32_dpp v176, v176, v176 quad_perm:[1,0,3,2] row_mask:0xf bank_mask:0xf
	s_nop 1
	v_add_f32_dpp v176, v176, v176 quad_perm:[2,3,0,1] row_mask:0xf bank_mask:0xf
	s_nop 1
	v_add_f32_dpp v176, v176, v176 row_half_mirror row_mask:0xf bank_mask:0xf
	s_nop 1
	v_add_f32_dpp v176, v176, v176 row_mirror row_mask:0xf bank_mask:0xf
	s_nop 1
	v_readlane_b32 s18, v176, 0
	v_readlane_b32 s19, v176, 16
	v_readlane_b32 s20, v176, 32
	v_readlane_b32 s21, v176, 48
	s_nop 1
	v_mov_b32_e32 v177, s19
	v_mov_b32_e32 v178, s21
	v_add_f32_e32 v177, s18, v177
	v_add_f32_e32 v178, s20, v178
	v_add_f32_e32 v176, v177, v178
	v_fmamk_f32 v176, v176, 0x3a800000, v210
	v_rsq_f32_e32 v180, v176
	s_nop 0
	v_pk_mul_f32 v[112:113], v[112:113], v[180:181] op_sel_hi:[1,0]
	v_pk_mul_f32 v[114:115], v[114:115], v[180:181] op_sel_hi:[1,0]
	v_pk_mul_f32 v[116:117], v[116:117], v[180:181] op_sel_hi:[1,0]
	v_pk_mul_f32 v[118:119], v[118:119], v[180:181] op_sel_hi:[1,0]
	v_pk_mul_f32 v[120:121], v[120:121], v[180:181] op_sel_hi:[1,0]
	v_pk_mul_f32 v[122:123], v[122:123], v[180:181] op_sel_hi:[1,0]
	v_pk_mul_f32 v[124:125], v[124:125], v[180:181] op_sel_hi:[1,0]
	v_pk_mul_f32 v[126:127], v[126:127], v[180:181] op_sel_hi:[1,0]
	v_pk_mul_f32 v[112:113], v[12:13], v[112:113]
	v_pk_mul_f32 v[114:115], v[14:15], v[114:115]
	v_pk_mul_f32 v[116:117], v[8:9], v[116:117]
	v_pk_mul_f32 v[118:119], v[10:11], v[118:119]
	v_pk_mul_f32 v[120:121], v[4:5], v[120:121]
	v_pk_mul_f32 v[122:123], v[6:7], v[122:123]
	v_pk_mul_f32 v[124:125], v[0:1], v[124:125]
	v_pk_mul_f32 v[126:127], v[2:3], v[126:127]
	s_waitcnt lgkmcnt(0)
	v_pk_add_f32 v[144:145], v[144:145], 1.0 op_sel_hi:[1,0]
	v_pk_add_f32 v[146:147], v[146:147], 1.0 op_sel_hi:[1,0]
	v_pk_fma_f32 v[112:113], v[144:145], v[112:113], v[160:161]
	v_pk_fma_f32 v[114:115], v[146:147], v[114:115], v[162:163]
	v_cvt_pk_f16_f32 v112, v112, v113
	v_cvt_pk_f16_f32 v113, v114, v115
	global_store_dwordx2 v183, v[112:113], s[14:15] offset:0
	v_pk_add_f32 v[148:149], v[148:149], 1.0 op_sel_hi:[1,0]
	v_pk_add_f32 v[150:151], v[150:151], 1.0 op_sel_hi:[1,0]
	v_pk_fma_f32 v[116:117], v[148:149], v[116:117], v[164:165]
	v_pk_fma_f32 v[118:119], v[150:151], v[118:119], v[166:167]
	v_cvt_pk_f16_f32 v116, v116, v117
	v_cvt_pk_f16_f32 v117, v118, v119
	global_store_dwordx2 v183, v[116:117], s[14:15] offset:512
	v_pk_add_f32 v[152:153], v[152:153], 1.0 op_sel_hi:[1,0]
	v_pk_add_f32 v[154:155], v[154:155], 1.0 op_sel_hi:[1,0]
	v_pk_fma_f32 v[120:121], v[152:153], v[120:121], v[168:169]
	v_pk_fma_f32 v[122:123], v[154:155], v[122:123], v[170:171]
	v_cvt_pk_f16_f32 v120, v120, v121
	v_cvt_pk_f16_f32 v121, v122, v123
	global_store_dwordx2 v183, v[120:121], s[14:15] offset:1024
	v_pk_add_f32 v[156:157], v[156:157], 1.0 op_sel_hi:[1,0]
	v_pk_add_f32 v[158:159], v[158:159], 1.0 op_sel_hi:[1,0]
	v_pk_fma_f32 v[124:125], v[156:157], v[124:125], v[172:173]
	v_pk_fma_f32 v[126:127], v[158:159], v[126:127], v[174:175]
	v_cvt_pk_f16_f32 v124, v124, v125
	v_cvt_pk_f16_f32 v125, v126, v127
	global_store_dwordx2 v183, v[124:125], s[14:15] offset:1536
	s_add_u32 s14, s14, 0x400000
	s_addc_u32 s15, s15, 0
	s_waitcnt vmcnt(28)
	ds_read_b128 v[144:147], v184 offset:57344
	ds_read_b128 v[148:151], v184 offset:58368
	ds_read_b128 v[152:155], v184 offset:59392
	ds_read_b128 v[156:159], v184 offset:60416
	ds_read_b128 v[160:163], v184 offset:61440
	ds_read_b128 v[164:167], v184 offset:62464
	ds_read_b128 v[168:171], v184 offset:63488
	ds_read_b128 v[172:175], v184 offset:64512
	v_mul_f32_e32 v176, v129, v129
	v_mul_f32_e32 v177, v133, v133
	v_mul_f32_e32 v178, v137, v137
	v_mul_f32_e32 v179, v141, v141
	v_fmac_f32_e32 v176, v128, v128
	v_fmac_f32_e32 v177, v132, v132
	v_fmac_f32_e32 v178, v136, v136
	v_fmac_f32_e32 v179, v140, v140
	v_fmac_f32_e32 v176, v130, v130
	v_fmac_f32_e32 v177, v134, v134
	v_fmac_f32_e32 v178, v138, v138
	v_fmac_f32_e32 v179, v142, v142
	v_fmac_f32_e32 v176, v131, v131
	v_fmac_f32_e32 v177, v135, v135
	v_fmac_f32_e32 v178, v139, v139
	v_fmac_f32_e32 v179, v143, v143
	v_add_f32_e32 v176, v177, v176
	v_add_f32_e32 v176, v178, v176
	v_add_f32_e32 v176, v179, v176
	s_nop 1
	v_add_f32_dpp v176, v176, v176 quad_perm:[1,0,3,2] row_mask:0xf bank_mask:0xf
	s_nop 1
	v_add_f32_dpp v176, v176, v176 quad_perm:[2,3,0,1] row_mask:0xf bank_mask:0xf
	s_nop 1
	v_add_f32_dpp v176, v176, v176 row_half_mirror row_mask:0xf bank_mask:0xf
	s_nop 1
	v_add_f32_dpp v176, v176, v176 row_mirror row_mask:0xf bank_mask:0xf
	s_nop 1
	v_readlane_b32 s18, v176, 0
	v_readlane_b32 s19, v176, 16
	v_readlane_b32 s20, v176, 32
	v_readlane_b32 s21, v176, 48
	s_nop 1
	v_mov_b32_e32 v177, s19
	v_mov_b32_e32 v178, s21
	v_add_f32_e32 v177, s18, v177
	v_add_f32_e32 v178, s20, v178
	v_add_f32_e32 v176, v177, v178
	v_fmamk_f32 v176, v176, 0x3a800000, v210
	v_rsq_f32_e32 v180, v176
	s_nop 0
	v_pk_mul_f32 v[128:129], v[128:129], v[180:181] op_sel_hi:[1,0]
	v_pk_mul_f32 v[130:131], v[130:131], v[180:181] op_sel_hi:[1,0]
	v_pk_mul_f32 v[132:133], v[132:133], v[180:181] op_sel_hi:[1,0]
	v_pk_mul_f32 v[134:135], v[134:135], v[180:181] op_sel_hi:[1,0]
	v_pk_mul_f32 v[136:137], v[136:137], v[180:181] op_sel_hi:[1,0]
	v_pk_mul_f32 v[138:139], v[138:139], v[180:181] op_sel_hi:[1,0]
	v_pk_mul_f32 v[140:141], v[140:141], v[180:181] op_sel_hi:[1,0]
	v_pk_mul_f32 v[142:143], v[142:143], v[180:181] op_sel_hi:[1,0]
	v_pk_mul_f32 v[128:129], v[12:13], v[128:129]
	v_pk_mul_f32 v[130:131], v[14:15], v[130:131]
	v_pk_mul_f32 v[132:133], v[8:9], v[132:133]
	v_pk_mul_f32 v[134:135], v[10:11], v[134:135]
	v_pk_mul_f32 v[136:137], v[4:5], v[136:137]
	v_pk_mul_f32 v[138:139], v[6:7], v[138:139]
	v_pk_mul_f32 v[140:141], v[0:1], v[140:141]
	v_pk_mul_f32 v[142:143], v[2:3], v[142:143]
	s_waitcnt lgkmcnt(0)
	v_pk_add_f32 v[144:145], v[144:145], 1.0 op_sel_hi:[1,0]
	v_pk_add_f32 v[146:147], v[146:147], 1.0 op_sel_hi:[1,0]
	v_pk_fma_f32 v[128:129], v[144:145], v[128:129], v[160:161]
	v_pk_fma_f32 v[130:131], v[146:147], v[130:131], v[162:163]
	v_cvt_pk_f16_f32 v128, v128, v129
	v_cvt_pk_f16_f32 v129, v130, v131
	global_store_dwordx2 v183, v[128:129], s[14:15] offset:0
	v_pk_add_f32 v[148:149], v[148:149], 1.0 op_sel_hi:[1,0]
	v_pk_add_f32 v[150:151], v[150:151], 1.0 op_sel_hi:[1,0]
	v_pk_fma_f32 v[132:133], v[148:149], v[132:133], v[164:165]
	v_pk_fma_f32 v[134:135], v[150:151], v[134:135], v[166:167]
	v_cvt_pk_f16_f32 v132, v132, v133
	v_cvt_pk_f16_f32 v133, v134, v135
	global_store_dwordx2 v183, v[132:133], s[14:15] offset:512
	v_pk_add_f32 v[152:153], v[152:153], 1.0 op_sel_hi:[1,0]
	v_pk_add_f32 v[154:155], v[154:155], 1.0 op_sel_hi:[1,0]
	v_pk_fma_f32 v[136:137], v[152:153], v[136:137], v[168:169]
	v_pk_fma_f32 v[138:139], v[154:155], v[138:139], v[170:171]
	v_cvt_pk_f16_f32 v136, v136, v137
	v_cvt_pk_f16_f32 v137, v138, v139
	global_store_dwordx2 v183, v[136:137], s[14:15] offset:1024
	v_pk_add_f32 v[156:157], v[156:157], 1.0 op_sel_hi:[1,0]
	v_pk_add_f32 v[158:159], v[158:159], 1.0 op_sel_hi:[1,0]
	v_pk_fma_f32 v[140:141], v[156:157], v[140:141], v[172:173]
	v_pk_fma_f32 v[142:143], v[158:159], v[142:143], v[174:175]
	v_cvt_pk_f16_f32 v140, v140, v141
	v_cvt_pk_f16_f32 v141, v142, v143
	global_store_dwordx2 v183, v[140:141], s[14:15] offset:1536
	v_mov_b32_e32 v72, v192
